# P5 merge-gate hook and epilogue restructured: gate loads pipelined 4 row groups deep / all up front, packed f32 muls; plus P7 epilogue change
# speedup vs baseline: 1.0139x; 1.0029x over previous
.LBB0_870:
	ds_read_b128 v[158:161], v168
	ds_read_b128 v[162:165], v168 offset:1024
	ds_read_b128 v[172:175], v168 offset:2048
	ds_read_b128 v[176:179], v168 offset:3072
	ds_read_b128 v[180:183], v169
	ds_read_b128 v[184:187], v169 offset:1024
	ds_read_b128 v[188:191], v169 offset:2048
	ds_read_b128 v[192:195], v169 offset:3072
	v_lshl_add_u64 v[196:197], v[132:133], 0, s[54:55]
	s_mov_b32 m0, s71
	v_lshl_add_u64 v[232:233], v[196:197], 0, s[16:17]
	v_lshl_add_u64 v[236:237], v[130:131], 0, s[54:55]
	ds_read_b128 v[200:203], v170
	ds_read_b128 v[204:207], v170 offset:1024
	ds_read_b128 v[208:211], v170 offset:2048
	ds_read_b128 v[212:215], v170 offset:3072
	ds_read_b128 v[216:219], v170 offset:4096
	ds_read_b128 v[220:223], v170 offset:5120
	ds_read_b128 v[224:227], v170 offset:6144
	ds_read_b128 v[228:231], v170 offset:7168
	global_load_lds_dwordx4 v[232:233], off
	v_lshl_add_u64 v[232:233], v[236:237], 0, s[16:17]
	s_mov_b32 m0, s72
	s_nop 0
	global_load_lds_dwordx4 v[232:233], off
	s_waitcnt vmcnt(8)
	s_waitcnt lgkmcnt(0)
	s_barrier
	s_setprio 1
	s_waitcnt lgkmcnt(0)
	v_mfma_f32_16x16x32_bf16 v[34:37], v[158:161], v[200:203], v[34:37]
	v_mfma_f32_16x16x32_bf16 v[30:33], v[172:175], v[200:203], v[30:33]
	v_mfma_f32_16x16x32_bf16 v[58:61], v[158:161], v[208:211], v[58:61]
	v_mfma_f32_16x16x32_bf16 v[54:57], v[172:175], v[208:211], v[54:57]
	v_mfma_f32_16x16x32_bf16 v[74:77], v[158:161], v[216:219], v[74:77]
	v_mfma_f32_16x16x32_bf16 v[70:73], v[172:175], v[216:219], v[70:73]
	v_mfma_f32_16x16x32_bf16 v[110:113], v[158:161], v[224:227], v[110:113]
	v_mfma_f32_16x16x32_bf16 v[106:109], v[172:175], v[224:227], v[106:109]
	v_mfma_f32_16x16x32_bf16 v[34:37], v[162:165], v[204:207], v[34:37]
	v_mfma_f32_16x16x32_bf16 v[30:33], v[176:179], v[204:207], v[30:33]
	v_mfma_f32_16x16x32_bf16 v[58:61], v[162:165], v[212:215], v[58:61]
	v_mfma_f32_16x16x32_bf16 v[54:57], v[176:179], v[212:215], v[54:57]
	v_mfma_f32_16x16x32_bf16 v[74:77], v[162:165], v[220:223], v[74:77]
	v_mfma_f32_16x16x32_bf16 v[70:73], v[176:179], v[220:223], v[70:73]
	v_mfma_f32_16x16x32_bf16 v[110:113], v[162:165], v[228:231], v[110:113]
	v_mfma_f32_16x16x32_bf16 v[106:109], v[176:179], v[228:231], v[106:109]
	s_setprio 0
	s_setprio 1
	v_mfma_f32_16x16x32_bf16 v[50:53], v[180:183], v[200:203], v[50:53]
	v_mfma_f32_16x16x32_bf16 v[62:65], v[188:191], v[200:203], v[62:65]
	v_mfma_f32_16x16x32_bf16 v[66:69], v[180:183], v[208:211], v[66:69]
	v_mfma_f32_16x16x32_bf16 v[78:81], v[188:191], v[208:211], v[78:81]
	v_mfma_f32_16x16x32_bf16 v[82:85], v[180:183], v[216:219], v[82:85]
	v_mfma_f32_16x16x32_bf16 v[102:105], v[188:191], v[216:219], v[102:105]
	v_mfma_f32_16x16x32_bf16 v[114:117], v[180:183], v[224:227], v[114:117]
	v_mfma_f32_16x16x32_bf16 v[126:129], v[188:191], v[224:227], v[126:129]
	v_mfma_f32_16x16x32_bf16 v[50:53], v[184:187], v[204:207], v[50:53]
	v_mfma_f32_16x16x32_bf16 v[62:65], v[192:195], v[204:207], v[62:65]
	v_mfma_f32_16x16x32_bf16 v[66:69], v[184:187], v[212:215], v[66:69]
	v_mfma_f32_16x16x32_bf16 v[78:81], v[192:195], v[212:215], v[78:81]
	v_mfma_f32_16x16x32_bf16 v[82:85], v[184:187], v[220:223], v[82:85]
	v_mfma_f32_16x16x32_bf16 v[102:105], v[192:195], v[220:223], v[102:105]
	v_mfma_f32_16x16x32_bf16 v[114:117], v[184:187], v[228:231], v[114:117]
	v_mfma_f32_16x16x32_bf16 v[126:129], v[192:195], v[228:231], v[126:129]
	s_setprio 0
	s_barrier
	v_lshl_add_u64 v[238:239], v[136:137], 0, s[54:55]
	s_mov_b32 m0, s73
	v_lshl_add_u64 v[232:233], v[238:239], 0, s[28:29]
	v_lshl_add_u64 v[240:241], v[134:135], 0, s[54:55]
	ds_read_b128 v[200:203], v170 offset:16384
	ds_read_b128 v[204:207], v170 offset:17408
	ds_read_b128 v[208:211], v170 offset:18432
	ds_read_b128 v[212:215], v170 offset:19456
	ds_read_b128 v[216:219], v170 offset:20480
	ds_read_b128 v[220:223], v170 offset:21504
	ds_read_b128 v[224:227], v170 offset:22528
	ds_read_b128 v[228:231], v170 offset:23552
	global_load_lds_dwordx4 v[232:233], off
	v_lshl_add_u64 v[232:233], v[240:241], 0, s[28:29]
	s_mov_b32 m0, s74
	s_add_i32 s76, s70, s20
	global_load_lds_dwordx4 v[232:233], off
	v_lshl_add_u64 v[232:233], v[238:239], 0, s[38:39]
	s_mov_b32 m0, s76
	s_add_i32 s77, s76, 0x2000
	global_load_lds_dwordx4 v[232:233], off
	v_lshl_add_u64 v[232:233], v[240:241], 0, s[38:39]
	s_mov_b32 m0, s77
	s_nop 0
	global_load_lds_dwordx4 v[232:233], off
	v_lshl_add_u64 v[232:233], v[196:197], 0, s[28:29]
	s_mov_b32 m0, s21
	s_nop 0
	global_load_lds_dwordx4 v[232:233], off
	v_lshl_add_u64 v[232:233], v[236:237], 0, s[28:29]
	s_mov_b32 m0, s64
	s_nop 0
	global_load_lds_dwordx4 v[232:233], off
	s_waitcnt vmcnt(8)
	s_waitcnt lgkmcnt(0)
	s_barrier
	s_setprio 1
	s_waitcnt lgkmcnt(0)
	v_mfma_f32_16x16x32_bf16 v[122:125], v[158:161], v[200:203], v[122:125]
	v_mfma_f32_16x16x32_bf16 v[118:121], v[172:175], v[200:203], v[118:121]
	v_mfma_f32_16x16x32_bf16 v[90:93], v[158:161], v[208:211], v[90:93]
	v_mfma_f32_16x16x32_bf16 v[86:89], v[172:175], v[208:211], v[86:89]
	v_mfma_f32_16x16x32_bf16 v[38:41], v[158:161], v[216:219], v[38:41]
	v_mfma_f32_16x16x32_bf16 v[26:29], v[172:175], v[216:219], v[26:29]
	v_mfma_f32_16x16x32_bf16 v[14:17], v[158:161], v[224:227], v[14:17]
	v_mfma_f32_16x16x32_bf16 v[10:13], v[172:175], v[224:227], v[10:13]
	v_mfma_f32_16x16x32_bf16 v[122:125], v[162:165], v[204:207], v[122:125]
	v_mfma_f32_16x16x32_bf16 v[118:121], v[176:179], v[204:207], v[118:121]
	v_mfma_f32_16x16x32_bf16 v[90:93], v[162:165], v[212:215], v[90:93]
	v_mfma_f32_16x16x32_bf16 v[86:89], v[176:179], v[212:215], v[86:89]
	v_mfma_f32_16x16x32_bf16 v[38:41], v[162:165], v[220:223], v[38:41]
	v_mfma_f32_16x16x32_bf16 v[26:29], v[176:179], v[220:223], v[26:29]
	v_mfma_f32_16x16x32_bf16 v[14:17], v[162:165], v[228:231], v[14:17]
	v_mfma_f32_16x16x32_bf16 v[10:13], v[176:179], v[228:231], v[10:13]
	s_setprio 0
	s_setprio 1
	v_mfma_f32_16x16x32_bf16 v[98:101], v[180:183], v[200:203], v[98:101]
	v_mfma_f32_16x16x32_bf16 v[94:97], v[188:191], v[200:203], v[94:97]
	v_mfma_f32_16x16x32_bf16 v[46:49], v[180:183], v[208:211], v[46:49]
	v_mfma_f32_16x16x32_bf16 v[42:45], v[188:191], v[208:211], v[42:45]
	v_mfma_f32_16x16x32_bf16 v[22:25], v[180:183], v[216:219], v[22:25]
	v_mfma_f32_16x16x32_bf16 v[18:21], v[188:191], v[216:219], v[18:21]
	v_mfma_f32_16x16x32_bf16 v[6:9], v[180:183], v[224:227], v[6:9]
	v_mfma_f32_16x16x32_bf16 v[2:5], v[188:191], v[224:227], v[2:5]
	v_mfma_f32_16x16x32_bf16 v[98:101], v[184:187], v[204:207], v[98:101]
	v_mfma_f32_16x16x32_bf16 v[94:97], v[192:195], v[204:207], v[94:97]
	v_mfma_f32_16x16x32_bf16 v[46:49], v[184:187], v[212:215], v[46:49]
	v_mfma_f32_16x16x32_bf16 v[42:45], v[192:195], v[212:215], v[42:45]
	v_mfma_f32_16x16x32_bf16 v[22:25], v[184:187], v[220:223], v[22:25]
	v_mfma_f32_16x16x32_bf16 v[18:21], v[192:195], v[220:223], v[18:21]
	v_mfma_f32_16x16x32_bf16 v[6:9], v[184:187], v[228:231], v[6:9]
	v_mfma_f32_16x16x32_bf16 v[2:5], v[192:195], v[228:231], v[2:5]
	s_setprio 0
	s_barrier
	s_add_i32 s78, 0, 0x18000
	s_add_i32 s80, 0, 0x1c000
	v_add_u32_e32 v161, s78, v166
	v_add_u32_e32 v171, s80, v166
	ds_read_b128 v[162:165], v161
	ds_read_b128 v[172:175], v161 offset:1024
	ds_read_b128 v[176:179], v161 offset:2048
	ds_read_b128 v[180:183], v161 offset:3072
	ds_read_b128 v[184:187], v171
	ds_read_b128 v[188:191], v171 offset:1024
	ds_read_b128 v[192:195], v171 offset:2048
	ds_read_b128 v[200:203], v171 offset:3072
	s_mov_b32 m0, s65
	v_lshl_add_u64 v[158:159], v[196:197], 0, s[38:39]
	ds_read_b128 v[204:207], v170 offset:32768
	ds_read_b128 v[208:211], v170 offset:33792
	ds_read_b128 v[212:215], v170 offset:34816
	ds_read_b128 v[216:219], v170 offset:35840
	ds_read_b128 v[220:223], v170 offset:36864
	ds_read_b128 v[224:227], v170 offset:37888
	ds_read_b128 v[228:231], v170 offset:38912
	ds_read_b128 v[232:235], v170 offset:39936
	global_load_lds_dwordx4 v[158:159], off
	v_lshl_add_u64 v[158:159], v[236:237], 0, s[38:39]
	s_mov_b32 m0, s66
	s_nop 0
	global_load_lds_dwordx4 v[158:159], off
	s_waitcnt vmcnt(8)
	s_waitcnt lgkmcnt(0)
	s_barrier
	s_setprio 1
	s_waitcnt lgkmcnt(0)
	v_mfma_f32_16x16x32_bf16 v[34:37], v[162:165], v[204:207], v[34:37]
	v_mfma_f32_16x16x32_bf16 v[30:33], v[176:179], v[204:207], v[30:33]
	v_mfma_f32_16x16x32_bf16 v[58:61], v[162:165], v[212:215], v[58:61]
	v_mfma_f32_16x16x32_bf16 v[54:57], v[176:179], v[212:215], v[54:57]
	v_mfma_f32_16x16x32_bf16 v[74:77], v[162:165], v[220:223], v[74:77]
	v_mfma_f32_16x16x32_bf16 v[70:73], v[176:179], v[220:223], v[70:73]
	v_mfma_f32_16x16x32_bf16 v[110:113], v[162:165], v[228:231], v[110:113]
	v_mfma_f32_16x16x32_bf16 v[106:109], v[176:179], v[228:231], v[106:109]
	v_mfma_f32_16x16x32_bf16 v[34:37], v[172:175], v[208:211], v[34:37]
	v_mfma_f32_16x16x32_bf16 v[30:33], v[180:183], v[208:211], v[30:33]
	v_mfma_f32_16x16x32_bf16 v[58:61], v[172:175], v[216:219], v[58:61]
	v_mfma_f32_16x16x32_bf16 v[54:57], v[180:183], v[216:219], v[54:57]
	v_mfma_f32_16x16x32_bf16 v[74:77], v[172:175], v[224:227], v[74:77]
	v_mfma_f32_16x16x32_bf16 v[70:73], v[180:183], v[224:227], v[70:73]
	v_mfma_f32_16x16x32_bf16 v[110:113], v[172:175], v[232:235], v[110:113]
	v_mfma_f32_16x16x32_bf16 v[106:109], v[180:183], v[232:235], v[106:109]
	s_setprio 0
	s_setprio 1
	v_mfma_f32_16x16x32_bf16 v[50:53], v[184:187], v[204:207], v[50:53]
	v_mfma_f32_16x16x32_bf16 v[62:65], v[192:195], v[204:207], v[62:65]
	v_mfma_f32_16x16x32_bf16 v[66:69], v[184:187], v[212:215], v[66:69]
	v_mfma_f32_16x16x32_bf16 v[78:81], v[192:195], v[212:215], v[78:81]
	v_mfma_f32_16x16x32_bf16 v[82:85], v[184:187], v[220:223], v[82:85]
	v_mfma_f32_16x16x32_bf16 v[102:105], v[192:195], v[220:223], v[102:105]
	v_mfma_f32_16x16x32_bf16 v[114:117], v[184:187], v[228:231], v[114:117]
	v_mfma_f32_16x16x32_bf16 v[126:129], v[192:195], v[228:231], v[126:129]
	v_mfma_f32_16x16x32_bf16 v[50:53], v[188:191], v[208:211], v[50:53]
	v_mfma_f32_16x16x32_bf16 v[62:65], v[200:203], v[208:211], v[62:65]
	v_mfma_f32_16x16x32_bf16 v[66:69], v[188:191], v[216:219], v[66:69]
	v_mfma_f32_16x16x32_bf16 v[78:81], v[200:203], v[216:219], v[78:81]
	v_mfma_f32_16x16x32_bf16 v[82:85], v[188:191], v[224:227], v[82:85]
	v_mfma_f32_16x16x32_bf16 v[102:105], v[200:203], v[224:227], v[102:105]
	v_mfma_f32_16x16x32_bf16 v[114:117], v[188:191], v[232:235], v[114:117]
	v_mfma_f32_16x16x32_bf16 v[126:129], v[200:203], v[232:235], v[126:129]
	s_setprio 0
	s_barrier
; template <class Epi, bool HOOK = false>
; DI void gemm_phase(LAS unsigned char* lds, const Gemm g, const StaticOrder& S, const Epi& E) {
;     ...
;         if constexpr (HOOK) {
;             for (int t = 0; t < (nt >> 1); t += 2) PG8_KBODY();
;             E.hook(acc, cur, wr, wc, fr, fq);
;             for (int t = (nt >> 1); t < nt; t += 2) PG8_KBODY();
;     DI void hook(Acc& acc, const Unit& u, int wr, int wc, int fr, int fq) const {
;         const int row0 = u.pm * 256 + wr * 64 + fr;
; #pragma unroll
;         for (int ai = 0; ai < 2; ++ai)
; #pragma unroll
;             for (int m = 0; m < 4; ++m) {
;                 const int r = row0 + ai * 128 + m * 16;
; #pragma unroll
;                 for (int bj = 0; bj < 2; ++bj) {
;                     const int c0 = u.pn * 256 + bj * 128 + wc * 32 + 8 * fq;
;                     const u32x4 ga = *(const u32x4*)(Z + (size_t)r * NZ + ZC_GM + c0), gb = *(const u32x4*)(Z + (size_t)r * NZ + ZC_GM + DM + c0);
	s_add_i32 s78, s78, s20
	v_lshl_add_u64 v[158:159], v[238:239], 0, s[42:43]
	s_mov_b32 m0, s78
	s_add_i32 s79, s78, 0x2000
	ds_read_b128 v[204:207], v170 offset:49152
	ds_read_b128 v[208:211], v170 offset:50176
	ds_read_b128 v[212:215], v170 offset:51200
	ds_read_b128 v[216:219], v170 offset:52224
	ds_read_b128 v[220:223], v170 offset:53248
	ds_read_b128 v[224:227], v170 offset:54272
	ds_read_b128 v[228:231], v170 offset:55296
	ds_read_b128 v[232:235], v170 offset:56320
	global_load_lds_dwordx4 v[158:159], off
	v_lshl_add_u64 v[158:159], v[240:241], 0, s[42:43]
	s_mov_b32 m0, s79
	s_add_i32 s80, s80, s20
	global_load_lds_dwordx4 v[158:159], off
	v_lshl_add_u64 v[158:159], v[238:239], 0, s[44:45]
	s_mov_b32 m0, s80
	s_add_i32 s81, s80, 0x2000
	global_load_lds_dwordx4 v[158:159], off
	v_lshl_add_u64 v[158:159], v[240:241], 0, s[44:45]
	s_mov_b32 m0, s81
	s_nop 0
	global_load_lds_dwordx4 v[158:159], off
	v_lshl_add_u64 v[158:159], v[196:197], 0, s[42:43]
	s_mov_b32 m0, s68
	s_nop 0
	global_load_lds_dwordx4 v[158:159], off
	v_lshl_add_u64 v[158:159], v[236:237], 0, s[42:43]
	s_mov_b32 m0, s69
	s_nop 0
	global_load_lds_dwordx4 v[158:159], off
	s_waitcnt vmcnt(8)
	s_waitcnt lgkmcnt(0)
	s_barrier
	s_setprio 1
	s_waitcnt lgkmcnt(0)
	v_mfma_f32_16x16x32_bf16 v[122:125], v[162:165], v[204:207], v[122:125]
	v_mfma_f32_16x16x32_bf16 v[118:121], v[176:179], v[204:207], v[118:121]
	v_mfma_f32_16x16x32_bf16 v[90:93], v[162:165], v[212:215], v[90:93]
	v_mfma_f32_16x16x32_bf16 v[86:89], v[176:179], v[212:215], v[86:89]
	v_mfma_f32_16x16x32_bf16 v[38:41], v[162:165], v[220:223], v[38:41]
	v_mfma_f32_16x16x32_bf16 v[26:29], v[176:179], v[220:223], v[26:29]
	v_mfma_f32_16x16x32_bf16 v[14:17], v[162:165], v[228:231], v[14:17]
	v_mfma_f32_16x16x32_bf16 v[10:13], v[176:179], v[228:231], v[10:13]
	v_mfma_f32_16x16x32_bf16 v[122:125], v[172:175], v[208:211], v[122:125]
	v_mfma_f32_16x16x32_bf16 v[118:121], v[180:183], v[208:211], v[118:121]
	v_mfma_f32_16x16x32_bf16 v[90:93], v[172:175], v[216:219], v[90:93]
	v_mfma_f32_16x16x32_bf16 v[86:89], v[180:183], v[216:219], v[86:89]
	v_mfma_f32_16x16x32_bf16 v[38:41], v[172:175], v[224:227], v[38:41]
	v_mfma_f32_16x16x32_bf16 v[26:29], v[180:183], v[224:227], v[26:29]
	v_mfma_f32_16x16x32_bf16 v[14:17], v[172:175], v[232:235], v[14:17]
	v_mfma_f32_16x16x32_bf16 v[10:13], v[180:183], v[232:235], v[10:13]
	s_setprio 0
	s_setprio 1
	v_mfma_f32_16x16x32_bf16 v[98:101], v[184:187], v[204:207], v[98:101]
	v_mfma_f32_16x16x32_bf16 v[94:97], v[192:195], v[204:207], v[94:97]
	v_mfma_f32_16x16x32_bf16 v[46:49], v[184:187], v[212:215], v[46:49]
	v_mfma_f32_16x16x32_bf16 v[42:45], v[192:195], v[212:215], v[42:45]
	v_mfma_f32_16x16x32_bf16 v[22:25], v[184:187], v[220:223], v[22:25]
	v_mfma_f32_16x16x32_bf16 v[18:21], v[192:195], v[220:223], v[18:21]
	v_mfma_f32_16x16x32_bf16 v[6:9], v[184:187], v[228:231], v[6:9]
	v_mfma_f32_16x16x32_bf16 v[2:5], v[192:195], v[228:231], v[2:5]
	v_mfma_f32_16x16x32_bf16 v[98:101], v[188:191], v[208:211], v[98:101]
	v_mfma_f32_16x16x32_bf16 v[94:97], v[200:203], v[208:211], v[94:97]
	v_mfma_f32_16x16x32_bf16 v[46:49], v[188:191], v[216:219], v[46:49]
	v_mfma_f32_16x16x32_bf16 v[42:45], v[200:203], v[216:219], v[42:45]
	v_mfma_f32_16x16x32_bf16 v[22:25], v[188:191], v[224:227], v[22:25]
	v_mfma_f32_16x16x32_bf16 v[18:21], v[200:203], v[224:227], v[18:21]
	v_mfma_f32_16x16x32_bf16 v[6:9], v[188:191], v[232:235], v[6:9]
	v_mfma_f32_16x16x32_bf16 v[2:5], v[200:203], v[232:235], v[2:5]
	s_setprio 0
	s_barrier
	s_add_i32 s51, s51, 2
	s_add_u32 s54, s54, 0x100
	s_addc_u32 s55, s55, 0
	s_cmp_gt_u32 s51, 5
	s_cbranch_scc0 .LBB0_870
	v_lshl_add_u32 v160, s62, 8, v1
	v_lshl_or_b32 v130, s53, 8, v167
	s_ashr_i32 s53, s52, 31
	s_ashr_i32 s51, s50, 31
	s_lshl_b64 s[54:55], s[52:53], 19
	s_lshl_b64 s[56:57], s[50:51], 19
	s_add_u32 s54, s14, s54
	s_addc_u32 s55, s15, s55
	s_add_u32 s56, s40, s56
	s_addc_u32 s57, s41, s57
	s_and_b64 s[62:63], s[4:5], exec
	s_cselect_b32 s51, s55, s61
	s_cselect_b32 s53, s54, s60
	s_cselect_b32 s82, s57, s59
	s_cselect_b32 s83, s56, s58
	s_add_u32 s60, s60, 0x40480
	s_addc_u32 s61, s61, 0
	s_add_u32 s84, s58, 0x500
	s_addc_u32 s85, s59, 0
	s_mov_b32 s86, 6
	v_ashrrev_i32_e32 v131, 31, v130
	v_lshlrev_b64 v[158:159], 1, v[130:131]
	v_or_b32_e32 v132, 0x80, v130
	v_ashrrev_i32_e32 v133, 31, v132
	v_lshlrev_b64 v[162:163], 1, v[132:133]
	v_mad_u32_u24 v164, v160, s75, v158
	v_add_u32_e32 v164, 0x1200, v164
	v_mov_b32_e32 v248, 0xbfb8aa3b
	global_load_dwordx4 v[200:203], v164, s[22:23]
	global_load_dwordx4 v[204:207], v164, s[22:23] offset:2048
	global_load_dwordx4 v[208:211], v164, s[22:23] offset:256
	global_load_dwordx4 v[212:215], v164, s[22:23] offset:2304
	v_add_u32_e32 v165, 0x22000, v164
	global_load_dwordx4 v[216:219], v165, s[22:23]
	global_load_dwordx4 v[220:223], v165, s[22:23] offset:2048
	global_load_dwordx4 v[224:227], v165, s[22:23] offset:256
	global_load_dwordx4 v[228:231], v165, s[22:23] offset:2304
	v_add_u32_e32 v165, 0x44000, v164
	global_load_dwordx4 v[232:235], v165, s[22:23]
	global_load_dwordx4 v[236:239], v165, s[22:23] offset:2048
	global_load_dwordx4 v[240:243], v165, s[22:23] offset:256
	global_load_dwordx4 v[244:247], v165, s[22:23] offset:2304
	v_add_u32_e32 v165, 0x66000, v164
	global_load_dwordx4 v[172:175], v165, s[22:23]
	global_load_dwordx4 v[176:179], v165, s[22:23] offset:2048
	global_load_dwordx4 v[180:183], v165, s[22:23] offset:256
	global_load_dwordx4 v[184:187], v165, s[22:23] offset:2304
	s_waitcnt vmcnt(12)
;     DI void hook(Acc& acc, const Unit& u, int wr, int wc, int fr, int fq) const {
;         const int row0 = u.pm * 256 + wr * 64 + fr;
; #pragma unroll
;         for (int ai = 0; ai < 2; ++ai)
; #pragma unroll
;             for (int m = 0; m < 4; ++m) {
;                 const int r = row0 + ai * 128 + m * 16;
; #pragma unroll
;                 for (int bj = 0; bj < 2; ++bj) {
;                     const int c0 = u.pn * 256 + bj * 128 + wc * 32 + 8 * fq;
;                     const u32x4 ga = *(const u32x4*)(Z + (size_t)r * NZ + ZC_GM + c0), gb = *(const u32x4*)(Z + (size_t)r * NZ + ZC_GM + DM + c0);
;                     float ra[8];
;                     const unsigned gaw[4] = {ga.x, ga.y, ga.z, ga.w}, gbw[4] = {gb.x, gb.y, gb.z, gb.w};
; #pragma unroll
;                     for (int q = 0; q < 4; ++q) {
;                         ra[2 * q] = (1.0f + __expf(-bflo(gbw[q]))) * __builtin_amdgcn_rcpf(1.0f + __expf(-bflo(gaw[q])));
;                         ra[2 * q + 1] = (1.0f + __expf(-bfhi(gbw[q]))) * __builtin_amdgcn_rcpf(1.0f + __expf(-bfhi(gaw[q])));
;                     }
;                     acc[ai][bj][m][0] = acc[ai][bj][m][0] * (f32x4){ra[0], ra[1], ra[2], ra[3]};
;                     acc[ai][bj][m][1] = acc[ai][bj][m][1] * (f32x4){ra[4], ra[5], ra[6], ra[7]};
;                 }
;                 asm volatile("" ::: "memory");
	v_lshlrev_b32_e32 v188, 16, v200
	v_and_b32_e32 v189, 0xffff0000, v200
	v_lshlrev_b32_e32 v190, 16, v201
	v_and_b32_e32 v191, 0xffff0000, v201
	v_lshlrev_b32_e32 v192, 16, v202
	v_and_b32_e32 v193, 0xffff0000, v202
	v_lshlrev_b32_e32 v194, 16, v203
	v_and_b32_e32 v195, 0xffff0000, v203
	v_lshlrev_b32_e32 v130, 16, v204
	v_and_b32_e32 v131, 0xffff0000, v204
	v_lshlrev_b32_e32 v132, 16, v205
	v_and_b32_e32 v133, 0xffff0000, v205
	v_lshlrev_b32_e32 v134, 16, v206
	v_and_b32_e32 v135, 0xffff0000, v206
	v_lshlrev_b32_e32 v136, 16, v207
	v_and_b32_e32 v137, 0xffff0000, v207
	v_pk_mul_f32 v[188:189], v[188:189], v[248:249] op_sel_hi:[1,0]
	v_pk_mul_f32 v[190:191], v[190:191], v[248:249] op_sel_hi:[1,0]
	v_pk_mul_f32 v[192:193], v[192:193], v[248:249] op_sel_hi:[1,0]
	v_pk_mul_f32 v[194:195], v[194:195], v[248:249] op_sel_hi:[1,0]
	v_pk_mul_f32 v[130:131], v[130:131], v[248:249] op_sel_hi:[1,0]
	v_pk_mul_f32 v[132:133], v[132:133], v[248:249] op_sel_hi:[1,0]
	v_pk_mul_f32 v[134:135], v[134:135], v[248:249] op_sel_hi:[1,0]
	v_pk_mul_f32 v[136:137], v[136:137], v[248:249] op_sel_hi:[1,0]
	v_exp_f32_e32 v188, v188
	v_exp_f32_e32 v189, v189
	v_exp_f32_e32 v190, v190
	v_exp_f32_e32 v191, v191
	v_exp_f32_e32 v192, v192
	v_exp_f32_e32 v193, v193
	v_exp_f32_e32 v194, v194
	v_exp_f32_e32 v195, v195
	v_exp_f32_e32 v130, v130
	v_exp_f32_e32 v131, v131
	v_exp_f32_e32 v132, v132
	v_exp_f32_e32 v133, v133
	v_exp_f32_e32 v134, v134
	v_exp_f32_e32 v135, v135
	v_exp_f32_e32 v136, v136
	v_exp_f32_e32 v137, v137
	v_pk_add_f32 v[188:189], v[188:189], 1.0 op_sel_hi:[1,0]
	v_pk_add_f32 v[190:191], v[190:191], 1.0 op_sel_hi:[1,0]
	v_pk_add_f32 v[192:193], v[192:193], 1.0 op_sel_hi:[1,0]
	v_pk_add_f32 v[194:195], v[194:195], 1.0 op_sel_hi:[1,0]
	v_pk_add_f32 v[130:131], v[130:131], 1.0 op_sel_hi:[1,0]
	v_pk_add_f32 v[132:133], v[132:133], 1.0 op_sel_hi:[1,0]
	v_pk_add_f32 v[134:135], v[134:135], 1.0 op_sel_hi:[1,0]
	v_pk_add_f32 v[136:137], v[136:137], 1.0 op_sel_hi:[1,0]
	v_rcp_f32_e32 v188, v188
	v_rcp_f32_e32 v189, v189
	v_rcp_f32_e32 v190, v190
	v_rcp_f32_e32 v191, v191
	v_rcp_f32_e32 v192, v192
	v_rcp_f32_e32 v193, v193
	v_rcp_f32_e32 v194, v194
	v_rcp_f32_e32 v195, v195
	v_pk_mul_f32 v[130:131], v[130:131], v[188:189]
	v_pk_mul_f32 v[132:133], v[132:133], v[190:191]
	v_pk_mul_f32 v[134:135], v[134:135], v[192:193]
	v_pk_mul_f32 v[136:137], v[136:137], v[194:195]
	v_pk_mul_f32 v[34:35], v[34:35], v[130:131]
	v_pk_mul_f32 v[36:37], v[36:37], v[132:133]
	v_pk_mul_f32 v[30:31], v[30:31], v[134:135]
	v_pk_mul_f32 v[32:33], v[32:33], v[136:137]
	v_lshlrev_b32_e32 v188, 16, v208
	v_and_b32_e32 v189, 0xffff0000, v208
	v_lshlrev_b32_e32 v190, 16, v209
	v_and_b32_e32 v191, 0xffff0000, v209
	v_lshlrev_b32_e32 v192, 16, v210
	v_and_b32_e32 v193, 0xffff0000, v210
	v_lshlrev_b32_e32 v194, 16, v211
	v_and_b32_e32 v195, 0xffff0000, v211
	v_lshlrev_b32_e32 v130, 16, v212
	v_and_b32_e32 v131, 0xffff0000, v212
	v_lshlrev_b32_e32 v132, 16, v213
	v_and_b32_e32 v133, 0xffff0000, v213
	v_lshlrev_b32_e32 v134, 16, v214
	v_and_b32_e32 v135, 0xffff0000, v214
	v_lshlrev_b32_e32 v136, 16, v215
	v_and_b32_e32 v137, 0xffff0000, v215
	v_pk_mul_f32 v[188:189], v[188:189], v[248:249] op_sel_hi:[1,0]
	v_pk_mul_f32 v[190:191], v[190:191], v[248:249] op_sel_hi:[1,0]
	v_pk_mul_f32 v[192:193], v[192:193], v[248:249] op_sel_hi:[1,0]
	v_pk_mul_f32 v[194:195], v[194:195], v[248:249] op_sel_hi:[1,0]
	v_pk_mul_f32 v[130:131], v[130:131], v[248:249] op_sel_hi:[1,0]
	v_pk_mul_f32 v[132:133], v[132:133], v[248:249] op_sel_hi:[1,0]
	v_pk_mul_f32 v[134:135], v[134:135], v[248:249] op_sel_hi:[1,0]
	v_pk_mul_f32 v[136:137], v[136:137], v[248:249] op_sel_hi:[1,0]
	v_exp_f32_e32 v188, v188
	v_exp_f32_e32 v189, v189
	v_exp_f32_e32 v190, v190
	v_exp_f32_e32 v191, v191
	v_exp_f32_e32 v192, v192
	v_exp_f32_e32 v193, v193
	v_exp_f32_e32 v194, v194
	v_exp_f32_e32 v195, v195
	v_exp_f32_e32 v130, v130
	v_exp_f32_e32 v131, v131
	v_exp_f32_e32 v132, v132
	v_exp_f32_e32 v133, v133
	v_exp_f32_e32 v134, v134
	v_exp_f32_e32 v135, v135
	v_exp_f32_e32 v136, v136
	v_exp_f32_e32 v137, v137
	v_pk_add_f32 v[188:189], v[188:189], 1.0 op_sel_hi:[1,0]
	v_pk_add_f32 v[190:191], v[190:191], 1.0 op_sel_hi:[1,0]
	v_pk_add_f32 v[192:193], v[192:193], 1.0 op_sel_hi:[1,0]
	v_pk_add_f32 v[194:195], v[194:195], 1.0 op_sel_hi:[1,0]
	v_pk_add_f32 v[130:131], v[130:131], 1.0 op_sel_hi:[1,0]
	v_pk_add_f32 v[132:133], v[132:133], 1.0 op_sel_hi:[1,0]
	v_pk_add_f32 v[134:135], v[134:135], 1.0 op_sel_hi:[1,0]
	v_pk_add_f32 v[136:137], v[136:137], 1.0 op_sel_hi:[1,0]
	v_rcp_f32_e32 v188, v188
	v_rcp_f32_e32 v189, v189
	v_rcp_f32_e32 v190, v190
	v_rcp_f32_e32 v191, v191
	v_rcp_f32_e32 v192, v192
	v_rcp_f32_e32 v193, v193
	v_rcp_f32_e32 v194, v194
	v_rcp_f32_e32 v195, v195
	v_pk_mul_f32 v[130:131], v[130:131], v[188:189]
	v_pk_mul_f32 v[132:133], v[132:133], v[190:191]
	v_pk_mul_f32 v[134:135], v[134:135], v[192:193]
	v_pk_mul_f32 v[136:137], v[136:137], v[194:195]
	v_pk_mul_f32 v[50:51], v[50:51], v[130:131]
	v_pk_mul_f32 v[52:53], v[52:53], v[132:133]
	v_pk_mul_f32 v[62:63], v[62:63], v[134:135]
	v_pk_mul_f32 v[64:65], v[64:65], v[136:137]
	v_add_u32_e32 v165, 0x110000, v164
	global_load_dwordx4 v[200:203], v165, s[22:23]
	global_load_dwordx4 v[204:207], v165, s[22:23] offset:2048
	global_load_dwordx4 v[208:211], v165, s[22:23] offset:256
	global_load_dwordx4 v[212:215], v165, s[22:23] offset:2304
	s_waitcnt vmcnt(12)
;     DI void hook(Acc& acc, const Unit& u, int wr, int wc, int fr, int fq) const {
;         const int row0 = u.pm * 256 + wr * 64 + fr;
; #pragma unroll
;         for (int ai = 0; ai < 2; ++ai)
; #pragma unroll
;             for (int m = 0; m < 4; ++m) {
;                 const int r = row0 + ai * 128 + m * 16;
; #pragma unroll
;                 for (int bj = 0; bj < 2; ++bj) {
;                     const int c0 = u.pn * 256 + bj * 128 + wc * 32 + 8 * fq;
;                     const u32x4 ga = *(const u32x4*)(Z + (size_t)r * NZ + ZC_GM + c0), gb = *(const u32x4*)(Z + (size_t)r * NZ + ZC_GM + DM + c0);
;                     float ra[8];
;                     const unsigned gaw[4] = {ga.x, ga.y, ga.z, ga.w}, gbw[4] = {gb.x, gb.y, gb.z, gb.w};
; #pragma unroll
;                     for (int q = 0; q < 4; ++q) {
;                         ra[2 * q] = (1.0f + __expf(-bflo(gbw[q]))) * __builtin_amdgcn_rcpf(1.0f + __expf(-bflo(gaw[q])));
;                         ra[2 * q + 1] = (1.0f + __expf(-bfhi(gbw[q]))) * __builtin_amdgcn_rcpf(1.0f + __expf(-bfhi(gaw[q])));
;                     }
;                     acc[ai][bj][m][0] = acc[ai][bj][m][0] * (f32x4){ra[0], ra[1], ra[2], ra[3]};
;                     acc[ai][bj][m][1] = acc[ai][bj][m][1] * (f32x4){ra[4], ra[5], ra[6], ra[7]};
;                 }
;                 asm volatile("" ::: "memory");
	v_lshlrev_b32_e32 v188, 16, v216
	v_and_b32_e32 v189, 0xffff0000, v216
	v_lshlrev_b32_e32 v190, 16, v217
	v_and_b32_e32 v191, 0xffff0000, v217
	v_lshlrev_b32_e32 v192, 16, v218
	v_and_b32_e32 v193, 0xffff0000, v218
	v_lshlrev_b32_e32 v194, 16, v219
	v_and_b32_e32 v195, 0xffff0000, v219
	v_lshlrev_b32_e32 v130, 16, v220
	v_and_b32_e32 v131, 0xffff0000, v220
	v_lshlrev_b32_e32 v132, 16, v221
	v_and_b32_e32 v133, 0xffff0000, v221
	v_lshlrev_b32_e32 v134, 16, v222
	v_and_b32_e32 v135, 0xffff0000, v222
	v_lshlrev_b32_e32 v136, 16, v223
	v_and_b32_e32 v137, 0xffff0000, v223
	v_pk_mul_f32 v[188:189], v[188:189], v[248:249] op_sel_hi:[1,0]
	v_pk_mul_f32 v[190:191], v[190:191], v[248:249] op_sel_hi:[1,0]
	v_pk_mul_f32 v[192:193], v[192:193], v[248:249] op_sel_hi:[1,0]
	v_pk_mul_f32 v[194:195], v[194:195], v[248:249] op_sel_hi:[1,0]
	v_pk_mul_f32 v[130:131], v[130:131], v[248:249] op_sel_hi:[1,0]
	v_pk_mul_f32 v[132:133], v[132:133], v[248:249] op_sel_hi:[1,0]
	v_pk_mul_f32 v[134:135], v[134:135], v[248:249] op_sel_hi:[1,0]
	v_pk_mul_f32 v[136:137], v[136:137], v[248:249] op_sel_hi:[1,0]
	v_exp_f32_e32 v188, v188
	v_exp_f32_e32 v189, v189
	v_exp_f32_e32 v190, v190
	v_exp_f32_e32 v191, v191
	v_exp_f32_e32 v192, v192
	v_exp_f32_e32 v193, v193
	v_exp_f32_e32 v194, v194
	v_exp_f32_e32 v195, v195
	v_exp_f32_e32 v130, v130
	v_exp_f32_e32 v131, v131
	v_exp_f32_e32 v132, v132
	v_exp_f32_e32 v133, v133
	v_exp_f32_e32 v134, v134
	v_exp_f32_e32 v135, v135
	v_exp_f32_e32 v136, v136
	v_exp_f32_e32 v137, v137
	v_pk_add_f32 v[188:189], v[188:189], 1.0 op_sel_hi:[1,0]
	v_pk_add_f32 v[190:191], v[190:191], 1.0 op_sel_hi:[1,0]
	v_pk_add_f32 v[192:193], v[192:193], 1.0 op_sel_hi:[1,0]
	v_pk_add_f32 v[194:195], v[194:195], 1.0 op_sel_hi:[1,0]
	v_pk_add_f32 v[130:131], v[130:131], 1.0 op_sel_hi:[1,0]
	v_pk_add_f32 v[132:133], v[132:133], 1.0 op_sel_hi:[1,0]
	v_pk_add_f32 v[134:135], v[134:135], 1.0 op_sel_hi:[1,0]
	v_pk_add_f32 v[136:137], v[136:137], 1.0 op_sel_hi:[1,0]
	v_rcp_f32_e32 v188, v188
	v_rcp_f32_e32 v189, v189
	v_rcp_f32_e32 v190, v190
	v_rcp_f32_e32 v191, v191
	v_rcp_f32_e32 v192, v192
	v_rcp_f32_e32 v193, v193
	v_rcp_f32_e32 v194, v194
	v_rcp_f32_e32 v195, v195
	v_pk_mul_f32 v[130:131], v[130:131], v[188:189]
	v_pk_mul_f32 v[132:133], v[132:133], v[190:191]
	v_pk_mul_f32 v[134:135], v[134:135], v[192:193]
	v_pk_mul_f32 v[136:137], v[136:137], v[194:195]
	v_pk_mul_f32 v[58:59], v[58:59], v[130:131]
	v_pk_mul_f32 v[60:61], v[60:61], v[132:133]
	v_pk_mul_f32 v[54:55], v[54:55], v[134:135]
	v_pk_mul_f32 v[56:57], v[56:57], v[136:137]
	v_lshlrev_b32_e32 v188, 16, v224
	v_and_b32_e32 v189, 0xffff0000, v224
	v_lshlrev_b32_e32 v190, 16, v225
	v_and_b32_e32 v191, 0xffff0000, v225
	v_lshlrev_b32_e32 v192, 16, v226
	v_and_b32_e32 v193, 0xffff0000, v226
	v_lshlrev_b32_e32 v194, 16, v227
	v_and_b32_e32 v195, 0xffff0000, v227
	v_lshlrev_b32_e32 v130, 16, v228
	v_and_b32_e32 v131, 0xffff0000, v228
	v_lshlrev_b32_e32 v132, 16, v229
	v_and_b32_e32 v133, 0xffff0000, v229
	v_lshlrev_b32_e32 v134, 16, v230
	v_and_b32_e32 v135, 0xffff0000, v230
	v_lshlrev_b32_e32 v136, 16, v231
	v_and_b32_e32 v137, 0xffff0000, v231
	v_pk_mul_f32 v[188:189], v[188:189], v[248:249] op_sel_hi:[1,0]
	v_pk_mul_f32 v[190:191], v[190:191], v[248:249] op_sel_hi:[1,0]
	v_pk_mul_f32 v[192:193], v[192:193], v[248:249] op_sel_hi:[1,0]
	v_pk_mul_f32 v[194:195], v[194:195], v[248:249] op_sel_hi:[1,0]
	v_pk_mul_f32 v[130:131], v[130:131], v[248:249] op_sel_hi:[1,0]
	v_pk_mul_f32 v[132:133], v[132:133], v[248:249] op_sel_hi:[1,0]
	v_pk_mul_f32 v[134:135], v[134:135], v[248:249] op_sel_hi:[1,0]
	v_pk_mul_f32 v[136:137], v[136:137], v[248:249] op_sel_hi:[1,0]
	v_exp_f32_e32 v188, v188
	v_exp_f32_e32 v189, v189
	v_exp_f32_e32 v190, v190
	v_exp_f32_e32 v191, v191
	v_exp_f32_e32 v192, v192
	v_exp_f32_e32 v193, v193
	v_exp_f32_e32 v194, v194
	v_exp_f32_e32 v195, v195
	v_exp_f32_e32 v130, v130
	v_exp_f32_e32 v131, v131
	v_exp_f32_e32 v132, v132
	v_exp_f32_e32 v133, v133
	v_exp_f32_e32 v134, v134
	v_exp_f32_e32 v135, v135
	v_exp_f32_e32 v136, v136
	v_exp_f32_e32 v137, v137
	v_pk_add_f32 v[188:189], v[188:189], 1.0 op_sel_hi:[1,0]
	v_pk_add_f32 v[190:191], v[190:191], 1.0 op_sel_hi:[1,0]
	v_pk_add_f32 v[192:193], v[192:193], 1.0 op_sel_hi:[1,0]
	v_pk_add_f32 v[194:195], v[194:195], 1.0 op_sel_hi:[1,0]
	v_pk_add_f32 v[130:131], v[130:131], 1.0 op_sel_hi:[1,0]
	v_pk_add_f32 v[132:133], v[132:133], 1.0 op_sel_hi:[1,0]
	v_pk_add_f32 v[134:135], v[134:135], 1.0 op_sel_hi:[1,0]
	v_pk_add_f32 v[136:137], v[136:137], 1.0 op_sel_hi:[1,0]
	v_rcp_f32_e32 v188, v188
	v_rcp_f32_e32 v189, v189
	v_rcp_f32_e32 v190, v190
	v_rcp_f32_e32 v191, v191
	v_rcp_f32_e32 v192, v192
	v_rcp_f32_e32 v193, v193
	v_rcp_f32_e32 v194, v194
	v_rcp_f32_e32 v195, v195
	v_pk_mul_f32 v[130:131], v[130:131], v[188:189]
	v_pk_mul_f32 v[132:133], v[132:133], v[190:191]
	v_pk_mul_f32 v[134:135], v[134:135], v[192:193]
	v_pk_mul_f32 v[136:137], v[136:137], v[194:195]
	v_pk_mul_f32 v[66:67], v[66:67], v[130:131]
	v_pk_mul_f32 v[68:69], v[68:69], v[132:133]
	v_pk_mul_f32 v[78:79], v[78:79], v[134:135]
	v_pk_mul_f32 v[80:81], v[80:81], v[136:137]
	v_add_u32_e32 v165, 0x132000, v164
	global_load_dwordx4 v[216:219], v165, s[22:23]
	global_load_dwordx4 v[220:223], v165, s[22:23] offset:2048
	global_load_dwordx4 v[224:227], v165, s[22:23] offset:256
	global_load_dwordx4 v[228:231], v165, s[22:23] offset:2304
	s_waitcnt vmcnt(12)
;     DI void hook(Acc& acc, const Unit& u, int wr, int wc, int fr, int fq) const {
;         const int row0 = u.pm * 256 + wr * 64 + fr;
; #pragma unroll
;         for (int ai = 0; ai < 2; ++ai)
; #pragma unroll
;             for (int m = 0; m < 4; ++m) {
;                 const int r = row0 + ai * 128 + m * 16;
; #pragma unroll
;                 for (int bj = 0; bj < 2; ++bj) {
;                     const int c0 = u.pn * 256 + bj * 128 + wc * 32 + 8 * fq;
;                     const u32x4 ga = *(const u32x4*)(Z + (size_t)r * NZ + ZC_GM + c0), gb = *(const u32x4*)(Z + (size_t)r * NZ + ZC_GM + DM + c0);
;                     float ra[8];
;                     const unsigned gaw[4] = {ga.x, ga.y, ga.z, ga.w}, gbw[4] = {gb.x, gb.y, gb.z, gb.w};
; #pragma unroll
;                     for (int q = 0; q < 4; ++q) {
;                         ra[2 * q] = (1.0f + __expf(-bflo(gbw[q]))) * __builtin_amdgcn_rcpf(1.0f + __expf(-bflo(gaw[q])));
;                         ra[2 * q + 1] = (1.0f + __expf(-bfhi(gbw[q]))) * __builtin_amdgcn_rcpf(1.0f + __expf(-bfhi(gaw[q])));
;                     }
;                     acc[ai][bj][m][0] = acc[ai][bj][m][0] * (f32x4){ra[0], ra[1], ra[2], ra[3]};
;                     acc[ai][bj][m][1] = acc[ai][bj][m][1] * (f32x4){ra[4], ra[5], ra[6], ra[7]};
;                 }
;                 asm volatile("" ::: "memory");
	v_lshlrev_b32_e32 v188, 16, v232
	v_and_b32_e32 v189, 0xffff0000, v232
	v_lshlrev_b32_e32 v190, 16, v233
	v_and_b32_e32 v191, 0xffff0000, v233
	v_lshlrev_b32_e32 v192, 16, v234
	v_and_b32_e32 v193, 0xffff0000, v234
	v_lshlrev_b32_e32 v194, 16, v235
	v_and_b32_e32 v195, 0xffff0000, v235
	v_lshlrev_b32_e32 v130, 16, v236
	v_and_b32_e32 v131, 0xffff0000, v236
	v_lshlrev_b32_e32 v132, 16, v237
	v_and_b32_e32 v133, 0xffff0000, v237
	v_lshlrev_b32_e32 v134, 16, v238
	v_and_b32_e32 v135, 0xffff0000, v238
	v_lshlrev_b32_e32 v136, 16, v239
	v_and_b32_e32 v137, 0xffff0000, v239
	v_pk_mul_f32 v[188:189], v[188:189], v[248:249] op_sel_hi:[1,0]
	v_pk_mul_f32 v[190:191], v[190:191], v[248:249] op_sel_hi:[1,0]
	v_pk_mul_f32 v[192:193], v[192:193], v[248:249] op_sel_hi:[1,0]
	v_pk_mul_f32 v[194:195], v[194:195], v[248:249] op_sel_hi:[1,0]
	v_pk_mul_f32 v[130:131], v[130:131], v[248:249] op_sel_hi:[1,0]
	v_pk_mul_f32 v[132:133], v[132:133], v[248:249] op_sel_hi:[1,0]
	v_pk_mul_f32 v[134:135], v[134:135], v[248:249] op_sel_hi:[1,0]
	v_pk_mul_f32 v[136:137], v[136:137], v[248:249] op_sel_hi:[1,0]
	v_exp_f32_e32 v188, v188
	v_exp_f32_e32 v189, v189
	v_exp_f32_e32 v190, v190
	v_exp_f32_e32 v191, v191
	v_exp_f32_e32 v192, v192
	v_exp_f32_e32 v193, v193
	v_exp_f32_e32 v194, v194
	v_exp_f32_e32 v195, v195
	v_exp_f32_e32 v130, v130
	v_exp_f32_e32 v131, v131
	v_exp_f32_e32 v132, v132
	v_exp_f32_e32 v133, v133
	v_exp_f32_e32 v134, v134
	v_exp_f32_e32 v135, v135
	v_exp_f32_e32 v136, v136
	v_exp_f32_e32 v137, v137
	v_pk_add_f32 v[188:189], v[188:189], 1.0 op_sel_hi:[1,0]
	v_pk_add_f32 v[190:191], v[190:191], 1.0 op_sel_hi:[1,0]
	v_pk_add_f32 v[192:193], v[192:193], 1.0 op_sel_hi:[1,0]
	v_pk_add_f32 v[194:195], v[194:195], 1.0 op_sel_hi:[1,0]
	v_pk_add_f32 v[130:131], v[130:131], 1.0 op_sel_hi:[1,0]
	v_pk_add_f32 v[132:133], v[132:133], 1.0 op_sel_hi:[1,0]
	v_pk_add_f32 v[134:135], v[134:135], 1.0 op_sel_hi:[1,0]
	v_pk_add_f32 v[136:137], v[136:137], 1.0 op_sel_hi:[1,0]
	v_rcp_f32_e32 v188, v188
	v_rcp_f32_e32 v189, v189
	v_rcp_f32_e32 v190, v190
	v_rcp_f32_e32 v191, v191
	v_rcp_f32_e32 v192, v192
	v_rcp_f32_e32 v193, v193
	v_rcp_f32_e32 v194, v194
	v_rcp_f32_e32 v195, v195
	v_pk_mul_f32 v[130:131], v[130:131], v[188:189]
	v_pk_mul_f32 v[132:133], v[132:133], v[190:191]
	v_pk_mul_f32 v[134:135], v[134:135], v[192:193]
	v_pk_mul_f32 v[136:137], v[136:137], v[194:195]
	v_pk_mul_f32 v[74:75], v[74:75], v[130:131]
	v_pk_mul_f32 v[76:77], v[76:77], v[132:133]
	v_pk_mul_f32 v[70:71], v[70:71], v[134:135]
	v_pk_mul_f32 v[72:73], v[72:73], v[136:137]
	v_lshlrev_b32_e32 v188, 16, v240
	v_and_b32_e32 v189, 0xffff0000, v240
	v_lshlrev_b32_e32 v190, 16, v241
	v_and_b32_e32 v191, 0xffff0000, v241
	v_lshlrev_b32_e32 v192, 16, v242
	v_and_b32_e32 v193, 0xffff0000, v242
	v_lshlrev_b32_e32 v194, 16, v243
	v_and_b32_e32 v195, 0xffff0000, v243
	v_lshlrev_b32_e32 v130, 16, v244
	v_and_b32_e32 v131, 0xffff0000, v244
	v_lshlrev_b32_e32 v132, 16, v245
	v_and_b32_e32 v133, 0xffff0000, v245
	v_lshlrev_b32_e32 v134, 16, v246
	v_and_b32_e32 v135, 0xffff0000, v246
	v_lshlrev_b32_e32 v136, 16, v247
	v_and_b32_e32 v137, 0xffff0000, v247
	v_pk_mul_f32 v[188:189], v[188:189], v[248:249] op_sel_hi:[1,0]
	v_pk_mul_f32 v[190:191], v[190:191], v[248:249] op_sel_hi:[1,0]
	v_pk_mul_f32 v[192:193], v[192:193], v[248:249] op_sel_hi:[1,0]
	v_pk_mul_f32 v[194:195], v[194:195], v[248:249] op_sel_hi:[1,0]
	v_pk_mul_f32 v[130:131], v[130:131], v[248:249] op_sel_hi:[1,0]
	v_pk_mul_f32 v[132:133], v[132:133], v[248:249] op_sel_hi:[1,0]
	v_pk_mul_f32 v[134:135], v[134:135], v[248:249] op_sel_hi:[1,0]
	v_pk_mul_f32 v[136:137], v[136:137], v[248:249] op_sel_hi:[1,0]
	v_exp_f32_e32 v188, v188
	v_exp_f32_e32 v189, v189
	v_exp_f32_e32 v190, v190
	v_exp_f32_e32 v191, v191
	v_exp_f32_e32 v192, v192
	v_exp_f32_e32 v193, v193
	v_exp_f32_e32 v194, v194
	v_exp_f32_e32 v195, v195
	v_exp_f32_e32 v130, v130
	v_exp_f32_e32 v131, v131
	v_exp_f32_e32 v132, v132
	v_exp_f32_e32 v133, v133
	v_exp_f32_e32 v134, v134
	v_exp_f32_e32 v135, v135
	v_exp_f32_e32 v136, v136
	v_exp_f32_e32 v137, v137
	v_pk_add_f32 v[188:189], v[188:189], 1.0 op_sel_hi:[1,0]
	v_pk_add_f32 v[190:191], v[190:191], 1.0 op_sel_hi:[1,0]
	v_pk_add_f32 v[192:193], v[192:193], 1.0 op_sel_hi:[1,0]
	v_pk_add_f32 v[194:195], v[194:195], 1.0 op_sel_hi:[1,0]
	v_pk_add_f32 v[130:131], v[130:131], 1.0 op_sel_hi:[1,0]
	v_pk_add_f32 v[132:133], v[132:133], 1.0 op_sel_hi:[1,0]
	v_pk_add_f32 v[134:135], v[134:135], 1.0 op_sel_hi:[1,0]
	v_pk_add_f32 v[136:137], v[136:137], 1.0 op_sel_hi:[1,0]
	v_rcp_f32_e32 v188, v188
	v_rcp_f32_e32 v189, v189
	v_rcp_f32_e32 v190, v190
	v_rcp_f32_e32 v191, v191
	v_rcp_f32_e32 v192, v192
	v_rcp_f32_e32 v193, v193
	v_rcp_f32_e32 v194, v194
	v_rcp_f32_e32 v195, v195
	v_pk_mul_f32 v[130:131], v[130:131], v[188:189]
	v_pk_mul_f32 v[132:133], v[132:133], v[190:191]
	v_pk_mul_f32 v[134:135], v[134:135], v[192:193]
	v_pk_mul_f32 v[136:137], v[136:137], v[194:195]
	v_pk_mul_f32 v[82:83], v[82:83], v[130:131]
	v_pk_mul_f32 v[84:85], v[84:85], v[132:133]
	v_pk_mul_f32 v[102:103], v[102:103], v[134:135]
	v_pk_mul_f32 v[104:105], v[104:105], v[136:137]
	v_add_u32_e32 v165, 0x154000, v164
	global_load_dwordx4 v[232:235], v165, s[22:23]
	global_load_dwordx4 v[236:239], v165, s[22:23] offset:2048
	global_load_dwordx4 v[240:243], v165, s[22:23] offset:256
	global_load_dwordx4 v[244:247], v165, s[22:23] offset:2304
	s_waitcnt vmcnt(12)
;     DI void hook(Acc& acc, const Unit& u, int wr, int wc, int fr, int fq) const {
;         const int row0 = u.pm * 256 + wr * 64 + fr;
; #pragma unroll
;         for (int ai = 0; ai < 2; ++ai)
; #pragma unroll
;             for (int m = 0; m < 4; ++m) {
;                 const int r = row0 + ai * 128 + m * 16;
; #pragma unroll
;                 for (int bj = 0; bj < 2; ++bj) {
;                     const int c0 = u.pn * 256 + bj * 128 + wc * 32 + 8 * fq;
;                     const u32x4 ga = *(const u32x4*)(Z + (size_t)r * NZ + ZC_GM + c0), gb = *(const u32x4*)(Z + (size_t)r * NZ + ZC_GM + DM + c0);
;                     float ra[8];
;                     const unsigned gaw[4] = {ga.x, ga.y, ga.z, ga.w}, gbw[4] = {gb.x, gb.y, gb.z, gb.w};
; #pragma unroll
;                     for (int q = 0; q < 4; ++q) {
;                         ra[2 * q] = (1.0f + __expf(-bflo(gbw[q]))) * __builtin_amdgcn_rcpf(1.0f + __expf(-bflo(gaw[q])));
;                         ra[2 * q + 1] = (1.0f + __expf(-bfhi(gbw[q]))) * __builtin_amdgcn_rcpf(1.0f + __expf(-bfhi(gaw[q])));
;                     }
;                     acc[ai][bj][m][0] = acc[ai][bj][m][0] * (f32x4){ra[0], ra[1], ra[2], ra[3]};
;                     acc[ai][bj][m][1] = acc[ai][bj][m][1] * (f32x4){ra[4], ra[5], ra[6], ra[7]};
;                 }
;                 asm volatile("" ::: "memory");
	v_lshlrev_b32_e32 v188, 16, v172
	v_and_b32_e32 v189, 0xffff0000, v172
	v_lshlrev_b32_e32 v190, 16, v173
	v_and_b32_e32 v191, 0xffff0000, v173
	v_lshlrev_b32_e32 v192, 16, v174
	v_and_b32_e32 v193, 0xffff0000, v174
	v_lshlrev_b32_e32 v194, 16, v175
	v_and_b32_e32 v195, 0xffff0000, v175
	v_lshlrev_b32_e32 v130, 16, v176
	v_and_b32_e32 v131, 0xffff0000, v176
	v_lshlrev_b32_e32 v132, 16, v177
	v_and_b32_e32 v133, 0xffff0000, v177
	v_lshlrev_b32_e32 v134, 16, v178
	v_and_b32_e32 v135, 0xffff0000, v178
	v_lshlrev_b32_e32 v136, 16, v179
	v_and_b32_e32 v137, 0xffff0000, v179
	v_pk_mul_f32 v[188:189], v[188:189], v[248:249] op_sel_hi:[1,0]
	v_pk_mul_f32 v[190:191], v[190:191], v[248:249] op_sel_hi:[1,0]
	v_pk_mul_f32 v[192:193], v[192:193], v[248:249] op_sel_hi:[1,0]
	v_pk_mul_f32 v[194:195], v[194:195], v[248:249] op_sel_hi:[1,0]
	v_pk_mul_f32 v[130:131], v[130:131], v[248:249] op_sel_hi:[1,0]
	v_pk_mul_f32 v[132:133], v[132:133], v[248:249] op_sel_hi:[1,0]
	v_pk_mul_f32 v[134:135], v[134:135], v[248:249] op_sel_hi:[1,0]
	v_pk_mul_f32 v[136:137], v[136:137], v[248:249] op_sel_hi:[1,0]
	v_exp_f32_e32 v188, v188
	v_exp_f32_e32 v189, v189
	v_exp_f32_e32 v190, v190
	v_exp_f32_e32 v191, v191
	v_exp_f32_e32 v192, v192
	v_exp_f32_e32 v193, v193
	v_exp_f32_e32 v194, v194
	v_exp_f32_e32 v195, v195
	v_exp_f32_e32 v130, v130
	v_exp_f32_e32 v131, v131
	v_exp_f32_e32 v132, v132
	v_exp_f32_e32 v133, v133
	v_exp_f32_e32 v134, v134
	v_exp_f32_e32 v135, v135
	v_exp_f32_e32 v136, v136
	v_exp_f32_e32 v137, v137
	v_pk_add_f32 v[188:189], v[188:189], 1.0 op_sel_hi:[1,0]
	v_pk_add_f32 v[190:191], v[190:191], 1.0 op_sel_hi:[1,0]
	v_pk_add_f32 v[192:193], v[192:193], 1.0 op_sel_hi:[1,0]
	v_pk_add_f32 v[194:195], v[194:195], 1.0 op_sel_hi:[1,0]
	v_pk_add_f32 v[130:131], v[130:131], 1.0 op_sel_hi:[1,0]
	v_pk_add_f32 v[132:133], v[132:133], 1.0 op_sel_hi:[1,0]
	v_pk_add_f32 v[134:135], v[134:135], 1.0 op_sel_hi:[1,0]
	v_pk_add_f32 v[136:137], v[136:137], 1.0 op_sel_hi:[1,0]
	v_rcp_f32_e32 v188, v188
	v_rcp_f32_e32 v189, v189
	v_rcp_f32_e32 v190, v190
	v_rcp_f32_e32 v191, v191
	v_rcp_f32_e32 v192, v192
	v_rcp_f32_e32 v193, v193
	v_rcp_f32_e32 v194, v194
	v_rcp_f32_e32 v195, v195
	v_pk_mul_f32 v[130:131], v[130:131], v[188:189]
	v_pk_mul_f32 v[132:133], v[132:133], v[190:191]
	v_pk_mul_f32 v[134:135], v[134:135], v[192:193]
	v_pk_mul_f32 v[136:137], v[136:137], v[194:195]
	v_pk_mul_f32 v[110:111], v[110:111], v[130:131]
	v_pk_mul_f32 v[112:113], v[112:113], v[132:133]
	v_pk_mul_f32 v[106:107], v[106:107], v[134:135]
	v_pk_mul_f32 v[108:109], v[108:109], v[136:137]
	v_lshlrev_b32_e32 v188, 16, v180
	v_and_b32_e32 v189, 0xffff0000, v180
	v_lshlrev_b32_e32 v190, 16, v181
	v_and_b32_e32 v191, 0xffff0000, v181
	v_lshlrev_b32_e32 v192, 16, v182
	v_and_b32_e32 v193, 0xffff0000, v182
	v_lshlrev_b32_e32 v194, 16, v183
	v_and_b32_e32 v195, 0xffff0000, v183
	v_lshlrev_b32_e32 v130, 16, v184
	v_and_b32_e32 v131, 0xffff0000, v184
	v_lshlrev_b32_e32 v132, 16, v185
	v_and_b32_e32 v133, 0xffff0000, v185
	v_lshlrev_b32_e32 v134, 16, v186
	v_and_b32_e32 v135, 0xffff0000, v186
	v_lshlrev_b32_e32 v136, 16, v187
	v_and_b32_e32 v137, 0xffff0000, v187
	v_pk_mul_f32 v[188:189], v[188:189], v[248:249] op_sel_hi:[1,0]
	v_pk_mul_f32 v[190:191], v[190:191], v[248:249] op_sel_hi:[1,0]
	v_pk_mul_f32 v[192:193], v[192:193], v[248:249] op_sel_hi:[1,0]
	v_pk_mul_f32 v[194:195], v[194:195], v[248:249] op_sel_hi:[1,0]
	v_pk_mul_f32 v[130:131], v[130:131], v[248:249] op_sel_hi:[1,0]
	v_pk_mul_f32 v[132:133], v[132:133], v[248:249] op_sel_hi:[1,0]
	v_pk_mul_f32 v[134:135], v[134:135], v[248:249] op_sel_hi:[1,0]
	v_pk_mul_f32 v[136:137], v[136:137], v[248:249] op_sel_hi:[1,0]
	v_exp_f32_e32 v188, v188
	v_exp_f32_e32 v189, v189
	v_exp_f32_e32 v190, v190
	v_exp_f32_e32 v191, v191
	v_exp_f32_e32 v192, v192
	v_exp_f32_e32 v193, v193
	v_exp_f32_e32 v194, v194
	v_exp_f32_e32 v195, v195
	v_exp_f32_e32 v130, v130
	v_exp_f32_e32 v131, v131
	v_exp_f32_e32 v132, v132
	v_exp_f32_e32 v133, v133
	v_exp_f32_e32 v134, v134
	v_exp_f32_e32 v135, v135
	v_exp_f32_e32 v136, v136
	v_exp_f32_e32 v137, v137
	v_pk_add_f32 v[188:189], v[188:189], 1.0 op_sel_hi:[1,0]
	v_pk_add_f32 v[190:191], v[190:191], 1.0 op_sel_hi:[1,0]
	v_pk_add_f32 v[192:193], v[192:193], 1.0 op_sel_hi:[1,0]
	v_pk_add_f32 v[194:195], v[194:195], 1.0 op_sel_hi:[1,0]
	v_pk_add_f32 v[130:131], v[130:131], 1.0 op_sel_hi:[1,0]
	v_pk_add_f32 v[132:133], v[132:133], 1.0 op_sel_hi:[1,0]
	v_pk_add_f32 v[134:135], v[134:135], 1.0 op_sel_hi:[1,0]
	v_pk_add_f32 v[136:137], v[136:137], 1.0 op_sel_hi:[1,0]
	v_rcp_f32_e32 v188, v188
	v_rcp_f32_e32 v189, v189
	v_rcp_f32_e32 v190, v190
	v_rcp_f32_e32 v191, v191
	v_rcp_f32_e32 v192, v192
	v_rcp_f32_e32 v193, v193
	v_rcp_f32_e32 v194, v194
	v_rcp_f32_e32 v195, v195
	v_pk_mul_f32 v[130:131], v[130:131], v[188:189]
	v_pk_mul_f32 v[132:133], v[132:133], v[190:191]
	v_pk_mul_f32 v[134:135], v[134:135], v[192:193]
	v_pk_mul_f32 v[136:137], v[136:137], v[194:195]
	v_pk_mul_f32 v[114:115], v[114:115], v[130:131]
	v_pk_mul_f32 v[116:117], v[116:117], v[132:133]
	v_pk_mul_f32 v[126:127], v[126:127], v[134:135]
	v_pk_mul_f32 v[128:129], v[128:129], v[136:137]
	v_add_u32_e32 v165, 0x176000, v164
	global_load_dwordx4 v[172:175], v165, s[22:23]
	global_load_dwordx4 v[176:179], v165, s[22:23] offset:2048
	global_load_dwordx4 v[180:183], v165, s[22:23] offset:256
	global_load_dwordx4 v[184:187], v165, s[22:23] offset:2304
	s_waitcnt vmcnt(12)
;     DI void hook(Acc& acc, const Unit& u, int wr, int wc, int fr, int fq) const {
;     ...
;                     const int c0 = u.pn * 256 + bj * 128 + wc * 32 + 8 * fq;
;                     const u32x4 ga = *(const u32x4*)(Z + (size_t)r * NZ + ZC_GM + c0), gb = *(const u32x4*)(Z + (size_t)r * NZ + ZC_GM + DM + c0);
;                     float ra[8];
;                     const unsigned gaw[4] = {ga.x, ga.y, ga.z, ga.w}, gbw[4] = {gb.x, gb.y, gb.z, gb.w};
; #pragma unroll
;                     for (int q = 0; q < 4; ++q) {
;                         ra[2 * q] = (1.0f + __expf(-bflo(gbw[q]))) * __builtin_amdgcn_rcpf(1.0f + __expf(-bflo(gaw[q])));
;                         ra[2 * q + 1] = (1.0f + __expf(-bfhi(gbw[q]))) * __builtin_amdgcn_rcpf(1.0f + __expf(-bfhi(gaw[q])));
;                     }
;                     acc[ai][bj][m][0] = acc[ai][bj][m][0] * (f32x4){ra[0], ra[1], ra[2], ra[3]};
;                     acc[ai][bj][m][1] = acc[ai][bj][m][1] * (f32x4){ra[4], ra[5], ra[6], ra[7]};
	v_lshlrev_b32_e32 v188, 16, v200
	v_and_b32_e32 v189, 0xffff0000, v200
	v_lshlrev_b32_e32 v190, 16, v201
	v_and_b32_e32 v191, 0xffff0000, v201
	v_lshlrev_b32_e32 v192, 16, v202
	v_and_b32_e32 v193, 0xffff0000, v202
	v_lshlrev_b32_e32 v194, 16, v203
	v_and_b32_e32 v195, 0xffff0000, v203
	v_lshlrev_b32_e32 v130, 16, v204
	v_and_b32_e32 v131, 0xffff0000, v204
	v_lshlrev_b32_e32 v132, 16, v205
	v_and_b32_e32 v133, 0xffff0000, v205
	v_lshlrev_b32_e32 v134, 16, v206
	v_and_b32_e32 v135, 0xffff0000, v206
	v_lshlrev_b32_e32 v136, 16, v207
	v_and_b32_e32 v137, 0xffff0000, v207
	v_pk_mul_f32 v[188:189], v[188:189], v[248:249] op_sel_hi:[1,0]
	v_pk_mul_f32 v[190:191], v[190:191], v[248:249] op_sel_hi:[1,0]
	v_pk_mul_f32 v[192:193], v[192:193], v[248:249] op_sel_hi:[1,0]
	v_pk_mul_f32 v[194:195], v[194:195], v[248:249] op_sel_hi:[1,0]
	v_pk_mul_f32 v[130:131], v[130:131], v[248:249] op_sel_hi:[1,0]
	v_pk_mul_f32 v[132:133], v[132:133], v[248:249] op_sel_hi:[1,0]
	v_pk_mul_f32 v[134:135], v[134:135], v[248:249] op_sel_hi:[1,0]
	v_pk_mul_f32 v[136:137], v[136:137], v[248:249] op_sel_hi:[1,0]
	v_exp_f32_e32 v188, v188
	v_exp_f32_e32 v189, v189
	v_exp_f32_e32 v190, v190
	v_exp_f32_e32 v191, v191
	v_exp_f32_e32 v192, v192
	v_exp_f32_e32 v193, v193
	v_exp_f32_e32 v194, v194
	v_exp_f32_e32 v195, v195
	v_exp_f32_e32 v130, v130
	v_exp_f32_e32 v131, v131
	v_exp_f32_e32 v132, v132
	v_exp_f32_e32 v133, v133
	v_exp_f32_e32 v134, v134
	v_exp_f32_e32 v135, v135
	v_exp_f32_e32 v136, v136
	v_exp_f32_e32 v137, v137
	v_pk_add_f32 v[188:189], v[188:189], 1.0 op_sel_hi:[1,0]
	v_pk_add_f32 v[190:191], v[190:191], 1.0 op_sel_hi:[1,0]
	v_pk_add_f32 v[192:193], v[192:193], 1.0 op_sel_hi:[1,0]
	v_pk_add_f32 v[194:195], v[194:195], 1.0 op_sel_hi:[1,0]
	v_pk_add_f32 v[130:131], v[130:131], 1.0 op_sel_hi:[1,0]
	v_pk_add_f32 v[132:133], v[132:133], 1.0 op_sel_hi:[1,0]
	v_pk_add_f32 v[134:135], v[134:135], 1.0 op_sel_hi:[1,0]
	v_pk_add_f32 v[136:137], v[136:137], 1.0 op_sel_hi:[1,0]
	v_rcp_f32_e32 v188, v188
	v_rcp_f32_e32 v189, v189
	v_rcp_f32_e32 v190, v190
	v_rcp_f32_e32 v191, v191
	v_rcp_f32_e32 v192, v192
	v_rcp_f32_e32 v193, v193
	v_rcp_f32_e32 v194, v194
	v_rcp_f32_e32 v195, v195
	v_pk_mul_f32 v[130:131], v[130:131], v[188:189]
	v_pk_mul_f32 v[132:133], v[132:133], v[190:191]
	v_pk_mul_f32 v[134:135], v[134:135], v[192:193]
	v_pk_mul_f32 v[136:137], v[136:137], v[194:195]
	v_pk_mul_f32 v[122:123], v[122:123], v[130:131]
	v_pk_mul_f32 v[124:125], v[124:125], v[132:133]
	v_pk_mul_f32 v[118:119], v[118:119], v[134:135]
	v_pk_mul_f32 v[120:121], v[120:121], v[136:137]
	v_lshlrev_b32_e32 v188, 16, v208
	v_and_b32_e32 v189, 0xffff0000, v208
	v_lshlrev_b32_e32 v190, 16, v209
	v_and_b32_e32 v191, 0xffff0000, v209
	v_lshlrev_b32_e32 v192, 16, v210
	v_and_b32_e32 v193, 0xffff0000, v210
	v_lshlrev_b32_e32 v194, 16, v211
	v_and_b32_e32 v195, 0xffff0000, v211
	v_lshlrev_b32_e32 v130, 16, v212
	v_and_b32_e32 v131, 0xffff0000, v212
	v_lshlrev_b32_e32 v132, 16, v213
	v_and_b32_e32 v133, 0xffff0000, v213
	v_lshlrev_b32_e32 v134, 16, v214
	v_and_b32_e32 v135, 0xffff0000, v214
	v_lshlrev_b32_e32 v136, 16, v215
	v_and_b32_e32 v137, 0xffff0000, v215
	v_pk_mul_f32 v[188:189], v[188:189], v[248:249] op_sel_hi:[1,0]
	v_pk_mul_f32 v[190:191], v[190:191], v[248:249] op_sel_hi:[1,0]
	v_pk_mul_f32 v[192:193], v[192:193], v[248:249] op_sel_hi:[1,0]
	v_pk_mul_f32 v[194:195], v[194:195], v[248:249] op_sel_hi:[1,0]
	v_pk_mul_f32 v[130:131], v[130:131], v[248:249] op_sel_hi:[1,0]
	v_pk_mul_f32 v[132:133], v[132:133], v[248:249] op_sel_hi:[1,0]
	v_pk_mul_f32 v[134:135], v[134:135], v[248:249] op_sel_hi:[1,0]
	v_pk_mul_f32 v[136:137], v[136:137], v[248:249] op_sel_hi:[1,0]
	v_exp_f32_e32 v188, v188
	v_exp_f32_e32 v189, v189
	v_exp_f32_e32 v190, v190
	v_exp_f32_e32 v191, v191
	v_exp_f32_e32 v192, v192
	v_exp_f32_e32 v193, v193
	v_exp_f32_e32 v194, v194
	v_exp_f32_e32 v195, v195
	v_exp_f32_e32 v130, v130
	v_exp_f32_e32 v131, v131
	v_exp_f32_e32 v132, v132
	v_exp_f32_e32 v133, v133
	v_exp_f32_e32 v134, v134
	v_exp_f32_e32 v135, v135
	v_exp_f32_e32 v136, v136
	v_exp_f32_e32 v137, v137
	v_pk_add_f32 v[188:189], v[188:189], 1.0 op_sel_hi:[1,0]
	v_pk_add_f32 v[190:191], v[190:191], 1.0 op_sel_hi:[1,0]
	v_pk_add_f32 v[192:193], v[192:193], 1.0 op_sel_hi:[1,0]
	v_pk_add_f32 v[194:195], v[194:195], 1.0 op_sel_hi:[1,0]
	v_pk_add_f32 v[130:131], v[130:131], 1.0 op_sel_hi:[1,0]
	v_pk_add_f32 v[132:133], v[132:133], 1.0 op_sel_hi:[1,0]
	v_pk_add_f32 v[134:135], v[134:135], 1.0 op_sel_hi:[1,0]
	v_pk_add_f32 v[136:137], v[136:137], 1.0 op_sel_hi:[1,0]
	v_rcp_f32_e32 v188, v188
	v_rcp_f32_e32 v189, v189
	v_rcp_f32_e32 v190, v190
	v_rcp_f32_e32 v191, v191
	v_rcp_f32_e32 v192, v192
	v_rcp_f32_e32 v193, v193
	v_rcp_f32_e32 v194, v194
	v_rcp_f32_e32 v195, v195
	v_pk_mul_f32 v[130:131], v[130:131], v[188:189]
	v_pk_mul_f32 v[132:133], v[132:133], v[190:191]
	v_pk_mul_f32 v[134:135], v[134:135], v[192:193]
	v_pk_mul_f32 v[136:137], v[136:137], v[194:195]
	v_pk_mul_f32 v[98:99], v[98:99], v[130:131]
	v_pk_mul_f32 v[100:101], v[100:101], v[132:133]
	v_pk_mul_f32 v[94:95], v[94:95], v[134:135]
	v_pk_mul_f32 v[96:97], v[96:97], v[136:137]
	s_waitcnt vmcnt(8)
;     DI void hook(Acc& acc, const Unit& u, int wr, int wc, int fr, int fq) const {
;     ...
;                     const int c0 = u.pn * 256 + bj * 128 + wc * 32 + 8 * fq;
;                     const u32x4 ga = *(const u32x4*)(Z + (size_t)r * NZ + ZC_GM + c0), gb = *(const u32x4*)(Z + (size_t)r * NZ + ZC_GM + DM + c0);
;                     float ra[8];
;                     const unsigned gaw[4] = {ga.x, ga.y, ga.z, ga.w}, gbw[4] = {gb.x, gb.y, gb.z, gb.w};
; #pragma unroll
;                     for (int q = 0; q < 4; ++q) {
;                         ra[2 * q] = (1.0f + __expf(-bflo(gbw[q]))) * __builtin_amdgcn_rcpf(1.0f + __expf(-bflo(gaw[q])));
;                         ra[2 * q + 1] = (1.0f + __expf(-bfhi(gbw[q]))) * __builtin_amdgcn_rcpf(1.0f + __expf(-bfhi(gaw[q])));
;                     }
;                     acc[ai][bj][m][0] = acc[ai][bj][m][0] * (f32x4){ra[0], ra[1], ra[2], ra[3]};
;                     acc[ai][bj][m][1] = acc[ai][bj][m][1] * (f32x4){ra[4], ra[5], ra[6], ra[7]};
	v_lshlrev_b32_e32 v188, 16, v216
	v_and_b32_e32 v189, 0xffff0000, v216
	v_lshlrev_b32_e32 v190, 16, v217
	v_and_b32_e32 v191, 0xffff0000, v217
	v_lshlrev_b32_e32 v192, 16, v218
	v_and_b32_e32 v193, 0xffff0000, v218
	v_lshlrev_b32_e32 v194, 16, v219
	v_and_b32_e32 v195, 0xffff0000, v219
	v_lshlrev_b32_e32 v130, 16, v220
	v_and_b32_e32 v131, 0xffff0000, v220
	v_lshlrev_b32_e32 v132, 16, v221
	v_and_b32_e32 v133, 0xffff0000, v221
	v_lshlrev_b32_e32 v134, 16, v222
	v_and_b32_e32 v135, 0xffff0000, v222
	v_lshlrev_b32_e32 v136, 16, v223
	v_and_b32_e32 v137, 0xffff0000, v223
	v_pk_mul_f32 v[188:189], v[188:189], v[248:249] op_sel_hi:[1,0]
	v_pk_mul_f32 v[190:191], v[190:191], v[248:249] op_sel_hi:[1,0]
	v_pk_mul_f32 v[192:193], v[192:193], v[248:249] op_sel_hi:[1,0]
	v_pk_mul_f32 v[194:195], v[194:195], v[248:249] op_sel_hi:[1,0]
	v_pk_mul_f32 v[130:131], v[130:131], v[248:249] op_sel_hi:[1,0]
	v_pk_mul_f32 v[132:133], v[132:133], v[248:249] op_sel_hi:[1,0]
	v_pk_mul_f32 v[134:135], v[134:135], v[248:249] op_sel_hi:[1,0]
	v_pk_mul_f32 v[136:137], v[136:137], v[248:249] op_sel_hi:[1,0]
	v_exp_f32_e32 v188, v188
	v_exp_f32_e32 v189, v189
	v_exp_f32_e32 v190, v190
	v_exp_f32_e32 v191, v191
	v_exp_f32_e32 v192, v192
	v_exp_f32_e32 v193, v193
	v_exp_f32_e32 v194, v194
	v_exp_f32_e32 v195, v195
	v_exp_f32_e32 v130, v130
	v_exp_f32_e32 v131, v131
	v_exp_f32_e32 v132, v132
	v_exp_f32_e32 v133, v133
	v_exp_f32_e32 v134, v134
	v_exp_f32_e32 v135, v135
	v_exp_f32_e32 v136, v136
	v_exp_f32_e32 v137, v137
	v_pk_add_f32 v[188:189], v[188:189], 1.0 op_sel_hi:[1,0]
	v_pk_add_f32 v[190:191], v[190:191], 1.0 op_sel_hi:[1,0]
	v_pk_add_f32 v[192:193], v[192:193], 1.0 op_sel_hi:[1,0]
	v_pk_add_f32 v[194:195], v[194:195], 1.0 op_sel_hi:[1,0]
	v_pk_add_f32 v[130:131], v[130:131], 1.0 op_sel_hi:[1,0]
	v_pk_add_f32 v[132:133], v[132:133], 1.0 op_sel_hi:[1,0]
	v_pk_add_f32 v[134:135], v[134:135], 1.0 op_sel_hi:[1,0]
	v_pk_add_f32 v[136:137], v[136:137], 1.0 op_sel_hi:[1,0]
	v_rcp_f32_e32 v188, v188
	v_rcp_f32_e32 v189, v189
	v_rcp_f32_e32 v190, v190
	v_rcp_f32_e32 v191, v191
	v_rcp_f32_e32 v192, v192
	v_rcp_f32_e32 v193, v193
	v_rcp_f32_e32 v194, v194
	v_rcp_f32_e32 v195, v195
	v_pk_mul_f32 v[130:131], v[130:131], v[188:189]
	v_pk_mul_f32 v[132:133], v[132:133], v[190:191]
	v_pk_mul_f32 v[134:135], v[134:135], v[192:193]
	v_pk_mul_f32 v[136:137], v[136:137], v[194:195]
	v_pk_mul_f32 v[90:91], v[90:91], v[130:131]
	v_pk_mul_f32 v[92:93], v[92:93], v[132:133]
	v_pk_mul_f32 v[86:87], v[86:87], v[134:135]
	v_pk_mul_f32 v[88:89], v[88:89], v[136:137]
	v_lshlrev_b32_e32 v188, 16, v224
	v_and_b32_e32 v189, 0xffff0000, v224
	v_lshlrev_b32_e32 v190, 16, v225
	v_and_b32_e32 v191, 0xffff0000, v225
	v_lshlrev_b32_e32 v192, 16, v226
	v_and_b32_e32 v193, 0xffff0000, v226
	v_lshlrev_b32_e32 v194, 16, v227
	v_and_b32_e32 v195, 0xffff0000, v227
	v_lshlrev_b32_e32 v130, 16, v228
	v_and_b32_e32 v131, 0xffff0000, v228
	v_lshlrev_b32_e32 v132, 16, v229
	v_and_b32_e32 v133, 0xffff0000, v229
	v_lshlrev_b32_e32 v134, 16, v230
	v_and_b32_e32 v135, 0xffff0000, v230
	v_lshlrev_b32_e32 v136, 16, v231
	v_and_b32_e32 v137, 0xffff0000, v231
	v_pk_mul_f32 v[188:189], v[188:189], v[248:249] op_sel_hi:[1,0]
	v_pk_mul_f32 v[190:191], v[190:191], v[248:249] op_sel_hi:[1,0]
	v_pk_mul_f32 v[192:193], v[192:193], v[248:249] op_sel_hi:[1,0]
	v_pk_mul_f32 v[194:195], v[194:195], v[248:249] op_sel_hi:[1,0]
	v_pk_mul_f32 v[130:131], v[130:131], v[248:249] op_sel_hi:[1,0]
	v_pk_mul_f32 v[132:133], v[132:133], v[248:249] op_sel_hi:[1,0]
	v_pk_mul_f32 v[134:135], v[134:135], v[248:249] op_sel_hi:[1,0]
	v_pk_mul_f32 v[136:137], v[136:137], v[248:249] op_sel_hi:[1,0]
	v_exp_f32_e32 v188, v188
	v_exp_f32_e32 v189, v189
	v_exp_f32_e32 v190, v190
	v_exp_f32_e32 v191, v191
	v_exp_f32_e32 v192, v192
	v_exp_f32_e32 v193, v193
	v_exp_f32_e32 v194, v194
	v_exp_f32_e32 v195, v195
	v_exp_f32_e32 v130, v130
	v_exp_f32_e32 v131, v131
	v_exp_f32_e32 v132, v132
	v_exp_f32_e32 v133, v133
	v_exp_f32_e32 v134, v134
	v_exp_f32_e32 v135, v135
	v_exp_f32_e32 v136, v136
	v_exp_f32_e32 v137, v137
	v_pk_add_f32 v[188:189], v[188:189], 1.0 op_sel_hi:[1,0]
	v_pk_add_f32 v[190:191], v[190:191], 1.0 op_sel_hi:[1,0]
	v_pk_add_f32 v[192:193], v[192:193], 1.0 op_sel_hi:[1,0]
	v_pk_add_f32 v[194:195], v[194:195], 1.0 op_sel_hi:[1,0]
	v_pk_add_f32 v[130:131], v[130:131], 1.0 op_sel_hi:[1,0]
	v_pk_add_f32 v[132:133], v[132:133], 1.0 op_sel_hi:[1,0]
	v_pk_add_f32 v[134:135], v[134:135], 1.0 op_sel_hi:[1,0]
	v_pk_add_f32 v[136:137], v[136:137], 1.0 op_sel_hi:[1,0]
	v_rcp_f32_e32 v188, v188
	v_rcp_f32_e32 v189, v189
	v_rcp_f32_e32 v190, v190
	v_rcp_f32_e32 v191, v191
	v_rcp_f32_e32 v192, v192
	v_rcp_f32_e32 v193, v193
	v_rcp_f32_e32 v194, v194
	v_rcp_f32_e32 v195, v195
	v_pk_mul_f32 v[130:131], v[130:131], v[188:189]
	v_pk_mul_f32 v[132:133], v[132:133], v[190:191]
	v_pk_mul_f32 v[134:135], v[134:135], v[192:193]
	v_pk_mul_f32 v[136:137], v[136:137], v[194:195]
	v_pk_mul_f32 v[46:47], v[46:47], v[130:131]
	v_pk_mul_f32 v[48:49], v[48:49], v[132:133]
	v_pk_mul_f32 v[42:43], v[42:43], v[134:135]
	v_pk_mul_f32 v[44:45], v[44:45], v[136:137]
	s_waitcnt vmcnt(4)
;     DI void hook(Acc& acc, const Unit& u, int wr, int wc, int fr, int fq) const {
;     ...
;                     const int c0 = u.pn * 256 + bj * 128 + wc * 32 + 8 * fq;
;                     const u32x4 ga = *(const u32x4*)(Z + (size_t)r * NZ + ZC_GM + c0), gb = *(const u32x4*)(Z + (size_t)r * NZ + ZC_GM + DM + c0);
;                     float ra[8];
;                     const unsigned gaw[4] = {ga.x, ga.y, ga.z, ga.w}, gbw[4] = {gb.x, gb.y, gb.z, gb.w};
; #pragma unroll
;                     for (int q = 0; q < 4; ++q) {
;                         ra[2 * q] = (1.0f + __expf(-bflo(gbw[q]))) * __builtin_amdgcn_rcpf(1.0f + __expf(-bflo(gaw[q])));
;                         ra[2 * q + 1] = (1.0f + __expf(-bfhi(gbw[q]))) * __builtin_amdgcn_rcpf(1.0f + __expf(-bfhi(gaw[q])));
;                     }
;                     acc[ai][bj][m][0] = acc[ai][bj][m][0] * (f32x4){ra[0], ra[1], ra[2], ra[3]};
;                     acc[ai][bj][m][1] = acc[ai][bj][m][1] * (f32x4){ra[4], ra[5], ra[6], ra[7]};
	v_lshlrev_b32_e32 v188, 16, v232
	v_and_b32_e32 v189, 0xffff0000, v232
	v_lshlrev_b32_e32 v190, 16, v233
	v_and_b32_e32 v191, 0xffff0000, v233
	v_lshlrev_b32_e32 v192, 16, v234
	v_and_b32_e32 v193, 0xffff0000, v234
	v_lshlrev_b32_e32 v194, 16, v235
	v_and_b32_e32 v195, 0xffff0000, v235
	v_lshlrev_b32_e32 v130, 16, v236
	v_and_b32_e32 v131, 0xffff0000, v236
	v_lshlrev_b32_e32 v132, 16, v237
	v_and_b32_e32 v133, 0xffff0000, v237
	v_lshlrev_b32_e32 v134, 16, v238
	v_and_b32_e32 v135, 0xffff0000, v238
	v_lshlrev_b32_e32 v136, 16, v239
	v_and_b32_e32 v137, 0xffff0000, v239
	v_pk_mul_f32 v[188:189], v[188:189], v[248:249] op_sel_hi:[1,0]
	v_pk_mul_f32 v[190:191], v[190:191], v[248:249] op_sel_hi:[1,0]
	v_pk_mul_f32 v[192:193], v[192:193], v[248:249] op_sel_hi:[1,0]
	v_pk_mul_f32 v[194:195], v[194:195], v[248:249] op_sel_hi:[1,0]
	v_pk_mul_f32 v[130:131], v[130:131], v[248:249] op_sel_hi:[1,0]
	v_pk_mul_f32 v[132:133], v[132:133], v[248:249] op_sel_hi:[1,0]
	v_pk_mul_f32 v[134:135], v[134:135], v[248:249] op_sel_hi:[1,0]
	v_pk_mul_f32 v[136:137], v[136:137], v[248:249] op_sel_hi:[1,0]
	v_exp_f32_e32 v188, v188
	v_exp_f32_e32 v189, v189
	v_exp_f32_e32 v190, v190
	v_exp_f32_e32 v191, v191
	v_exp_f32_e32 v192, v192
	v_exp_f32_e32 v193, v193
	v_exp_f32_e32 v194, v194
	v_exp_f32_e32 v195, v195
	v_exp_f32_e32 v130, v130
	v_exp_f32_e32 v131, v131
	v_exp_f32_e32 v132, v132
	v_exp_f32_e32 v133, v133
	v_exp_f32_e32 v134, v134
	v_exp_f32_e32 v135, v135
	v_exp_f32_e32 v136, v136
	v_exp_f32_e32 v137, v137
	v_pk_add_f32 v[188:189], v[188:189], 1.0 op_sel_hi:[1,0]
	v_pk_add_f32 v[190:191], v[190:191], 1.0 op_sel_hi:[1,0]
	v_pk_add_f32 v[192:193], v[192:193], 1.0 op_sel_hi:[1,0]
	v_pk_add_f32 v[194:195], v[194:195], 1.0 op_sel_hi:[1,0]
	v_pk_add_f32 v[130:131], v[130:131], 1.0 op_sel_hi:[1,0]
	v_pk_add_f32 v[132:133], v[132:133], 1.0 op_sel_hi:[1,0]
	v_pk_add_f32 v[134:135], v[134:135], 1.0 op_sel_hi:[1,0]
	v_pk_add_f32 v[136:137], v[136:137], 1.0 op_sel_hi:[1,0]
	v_rcp_f32_e32 v188, v188
	v_rcp_f32_e32 v189, v189
	v_rcp_f32_e32 v190, v190
	v_rcp_f32_e32 v191, v191
	v_rcp_f32_e32 v192, v192
	v_rcp_f32_e32 v193, v193
	v_rcp_f32_e32 v194, v194
	v_rcp_f32_e32 v195, v195
	v_pk_mul_f32 v[130:131], v[130:131], v[188:189]
	v_pk_mul_f32 v[132:133], v[132:133], v[190:191]
	v_pk_mul_f32 v[134:135], v[134:135], v[192:193]
	v_pk_mul_f32 v[136:137], v[136:137], v[194:195]
	v_pk_mul_f32 v[38:39], v[38:39], v[130:131]
	v_pk_mul_f32 v[40:41], v[40:41], v[132:133]
	v_pk_mul_f32 v[26:27], v[26:27], v[134:135]
	v_pk_mul_f32 v[28:29], v[28:29], v[136:137]
	v_lshlrev_b32_e32 v188, 16, v240
	v_and_b32_e32 v189, 0xffff0000, v240
	v_lshlrev_b32_e32 v190, 16, v241
	v_and_b32_e32 v191, 0xffff0000, v241
	v_lshlrev_b32_e32 v192, 16, v242
	v_and_b32_e32 v193, 0xffff0000, v242
	v_lshlrev_b32_e32 v194, 16, v243
	v_and_b32_e32 v195, 0xffff0000, v243
	v_lshlrev_b32_e32 v130, 16, v244
	v_and_b32_e32 v131, 0xffff0000, v244
	v_lshlrev_b32_e32 v132, 16, v245
	v_and_b32_e32 v133, 0xffff0000, v245
	v_lshlrev_b32_e32 v134, 16, v246
	v_and_b32_e32 v135, 0xffff0000, v246
	v_lshlrev_b32_e32 v136, 16, v247
	v_and_b32_e32 v137, 0xffff0000, v247
	v_pk_mul_f32 v[188:189], v[188:189], v[248:249] op_sel_hi:[1,0]
	v_pk_mul_f32 v[190:191], v[190:191], v[248:249] op_sel_hi:[1,0]
	v_pk_mul_f32 v[192:193], v[192:193], v[248:249] op_sel_hi:[1,0]
	v_pk_mul_f32 v[194:195], v[194:195], v[248:249] op_sel_hi:[1,0]
	v_pk_mul_f32 v[130:131], v[130:131], v[248:249] op_sel_hi:[1,0]
	v_pk_mul_f32 v[132:133], v[132:133], v[248:249] op_sel_hi:[1,0]
	v_pk_mul_f32 v[134:135], v[134:135], v[248:249] op_sel_hi:[1,0]
	v_pk_mul_f32 v[136:137], v[136:137], v[248:249] op_sel_hi:[1,0]
	v_exp_f32_e32 v188, v188
	v_exp_f32_e32 v189, v189
	v_exp_f32_e32 v190, v190
	v_exp_f32_e32 v191, v191
	v_exp_f32_e32 v192, v192
	v_exp_f32_e32 v193, v193
	v_exp_f32_e32 v194, v194
	v_exp_f32_e32 v195, v195
	v_exp_f32_e32 v130, v130
	v_exp_f32_e32 v131, v131
	v_exp_f32_e32 v132, v132
	v_exp_f32_e32 v133, v133
	v_exp_f32_e32 v134, v134
	v_exp_f32_e32 v135, v135
	v_exp_f32_e32 v136, v136
	v_exp_f32_e32 v137, v137
	v_pk_add_f32 v[188:189], v[188:189], 1.0 op_sel_hi:[1,0]
	v_pk_add_f32 v[190:191], v[190:191], 1.0 op_sel_hi:[1,0]
	v_pk_add_f32 v[192:193], v[192:193], 1.0 op_sel_hi:[1,0]
	v_pk_add_f32 v[194:195], v[194:195], 1.0 op_sel_hi:[1,0]
	v_pk_add_f32 v[130:131], v[130:131], 1.0 op_sel_hi:[1,0]
	v_pk_add_f32 v[132:133], v[132:133], 1.0 op_sel_hi:[1,0]
	v_pk_add_f32 v[134:135], v[134:135], 1.0 op_sel_hi:[1,0]
	v_pk_add_f32 v[136:137], v[136:137], 1.0 op_sel_hi:[1,0]
	v_rcp_f32_e32 v188, v188
	v_rcp_f32_e32 v189, v189
	v_rcp_f32_e32 v190, v190
	v_rcp_f32_e32 v191, v191
	v_rcp_f32_e32 v192, v192
	v_rcp_f32_e32 v193, v193
	v_rcp_f32_e32 v194, v194
	v_rcp_f32_e32 v195, v195
	v_pk_mul_f32 v[130:131], v[130:131], v[188:189]
	v_pk_mul_f32 v[132:133], v[132:133], v[190:191]
	v_pk_mul_f32 v[134:135], v[134:135], v[192:193]
	v_pk_mul_f32 v[136:137], v[136:137], v[194:195]
	v_pk_mul_f32 v[22:23], v[22:23], v[130:131]
	v_pk_mul_f32 v[24:25], v[24:25], v[132:133]
	v_pk_mul_f32 v[18:19], v[18:19], v[134:135]
	v_pk_mul_f32 v[20:21], v[20:21], v[136:137]
	s_waitcnt vmcnt(0)
;     DI void hook(Acc& acc, const Unit& u, int wr, int wc, int fr, int fq) const {
;     ...
;                     const int c0 = u.pn * 256 + bj * 128 + wc * 32 + 8 * fq;
;                     const u32x4 ga = *(const u32x4*)(Z + (size_t)r * NZ + ZC_GM + c0), gb = *(const u32x4*)(Z + (size_t)r * NZ + ZC_GM + DM + c0);
;                     float ra[8];
;                     const unsigned gaw[4] = {ga.x, ga.y, ga.z, ga.w}, gbw[4] = {gb.x, gb.y, gb.z, gb.w};
; #pragma unroll
;                     for (int q = 0; q < 4; ++q) {
;                         ra[2 * q] = (1.0f + __expf(-bflo(gbw[q]))) * __builtin_amdgcn_rcpf(1.0f + __expf(-bflo(gaw[q])));
;                         ra[2 * q + 1] = (1.0f + __expf(-bfhi(gbw[q]))) * __builtin_amdgcn_rcpf(1.0f + __expf(-bfhi(gaw[q])));
;                     }
;                     acc[ai][bj][m][0] = acc[ai][bj][m][0] * (f32x4){ra[0], ra[1], ra[2], ra[3]};
;                     acc[ai][bj][m][1] = acc[ai][bj][m][1] * (f32x4){ra[4], ra[5], ra[6], ra[7]};
	v_lshlrev_b32_e32 v188, 16, v172
	v_and_b32_e32 v189, 0xffff0000, v172
	v_lshlrev_b32_e32 v190, 16, v173
	v_and_b32_e32 v191, 0xffff0000, v173
	v_lshlrev_b32_e32 v192, 16, v174
	v_and_b32_e32 v193, 0xffff0000, v174
	v_lshlrev_b32_e32 v194, 16, v175
	v_and_b32_e32 v195, 0xffff0000, v175
	v_lshlrev_b32_e32 v130, 16, v176
	v_and_b32_e32 v131, 0xffff0000, v176
	v_lshlrev_b32_e32 v132, 16, v177
	v_and_b32_e32 v133, 0xffff0000, v177
	v_lshlrev_b32_e32 v134, 16, v178
	v_and_b32_e32 v135, 0xffff0000, v178
	v_lshlrev_b32_e32 v136, 16, v179
	v_and_b32_e32 v137, 0xffff0000, v179
	v_pk_mul_f32 v[188:189], v[188:189], v[248:249] op_sel_hi:[1,0]
	v_pk_mul_f32 v[190:191], v[190:191], v[248:249] op_sel_hi:[1,0]
	v_pk_mul_f32 v[192:193], v[192:193], v[248:249] op_sel_hi:[1,0]
	v_pk_mul_f32 v[194:195], v[194:195], v[248:249] op_sel_hi:[1,0]
	v_pk_mul_f32 v[130:131], v[130:131], v[248:249] op_sel_hi:[1,0]
	v_pk_mul_f32 v[132:133], v[132:133], v[248:249] op_sel_hi:[1,0]
	v_pk_mul_f32 v[134:135], v[134:135], v[248:249] op_sel_hi:[1,0]
	v_pk_mul_f32 v[136:137], v[136:137], v[248:249] op_sel_hi:[1,0]
	v_exp_f32_e32 v188, v188
	v_exp_f32_e32 v189, v189
	v_exp_f32_e32 v190, v190
	v_exp_f32_e32 v191, v191
	v_exp_f32_e32 v192, v192
	v_exp_f32_e32 v193, v193
	v_exp_f32_e32 v194, v194
	v_exp_f32_e32 v195, v195
	v_exp_f32_e32 v130, v130
	v_exp_f32_e32 v131, v131
	v_exp_f32_e32 v132, v132
	v_exp_f32_e32 v133, v133
	v_exp_f32_e32 v134, v134
	v_exp_f32_e32 v135, v135
	v_exp_f32_e32 v136, v136
	v_exp_f32_e32 v137, v137
	v_pk_add_f32 v[188:189], v[188:189], 1.0 op_sel_hi:[1,0]
	v_pk_add_f32 v[190:191], v[190:191], 1.0 op_sel_hi:[1,0]
	v_pk_add_f32 v[192:193], v[192:193], 1.0 op_sel_hi:[1,0]
	v_pk_add_f32 v[194:195], v[194:195], 1.0 op_sel_hi:[1,0]
	v_pk_add_f32 v[130:131], v[130:131], 1.0 op_sel_hi:[1,0]
	v_pk_add_f32 v[132:133], v[132:133], 1.0 op_sel_hi:[1,0]
	v_pk_add_f32 v[134:135], v[134:135], 1.0 op_sel_hi:[1,0]
	v_pk_add_f32 v[136:137], v[136:137], 1.0 op_sel_hi:[1,0]
	v_rcp_f32_e32 v188, v188
	v_rcp_f32_e32 v189, v189
	v_rcp_f32_e32 v190, v190
	v_rcp_f32_e32 v191, v191
	v_rcp_f32_e32 v192, v192
	v_rcp_f32_e32 v193, v193
	v_rcp_f32_e32 v194, v194
	v_rcp_f32_e32 v195, v195
	v_pk_mul_f32 v[130:131], v[130:131], v[188:189]
	v_pk_mul_f32 v[132:133], v[132:133], v[190:191]
	v_pk_mul_f32 v[134:135], v[134:135], v[192:193]
	v_pk_mul_f32 v[136:137], v[136:137], v[194:195]
	v_pk_mul_f32 v[14:15], v[14:15], v[130:131]
	v_pk_mul_f32 v[16:17], v[16:17], v[132:133]
	v_pk_mul_f32 v[10:11], v[10:11], v[134:135]
	v_pk_mul_f32 v[12:13], v[12:13], v[136:137]
	v_lshlrev_b32_e32 v188, 16, v180
	v_and_b32_e32 v189, 0xffff0000, v180
	v_lshlrev_b32_e32 v190, 16, v181
	v_and_b32_e32 v191, 0xffff0000, v181
	v_lshlrev_b32_e32 v192, 16, v182
	v_and_b32_e32 v193, 0xffff0000, v182
	v_lshlrev_b32_e32 v194, 16, v183
	v_and_b32_e32 v195, 0xffff0000, v183
	v_lshlrev_b32_e32 v130, 16, v184
	v_and_b32_e32 v131, 0xffff0000, v184
	v_lshlrev_b32_e32 v132, 16, v185
	v_and_b32_e32 v133, 0xffff0000, v185
	v_lshlrev_b32_e32 v134, 16, v186
	v_and_b32_e32 v135, 0xffff0000, v186
	v_lshlrev_b32_e32 v136, 16, v187
	v_and_b32_e32 v137, 0xffff0000, v187
	v_pk_mul_f32 v[188:189], v[188:189], v[248:249] op_sel_hi:[1,0]
	v_pk_mul_f32 v[190:191], v[190:191], v[248:249] op_sel_hi:[1,0]
	v_pk_mul_f32 v[192:193], v[192:193], v[248:249] op_sel_hi:[1,0]
	v_pk_mul_f32 v[194:195], v[194:195], v[248:249] op_sel_hi:[1,0]
	v_pk_mul_f32 v[130:131], v[130:131], v[248:249] op_sel_hi:[1,0]
	v_pk_mul_f32 v[132:133], v[132:133], v[248:249] op_sel_hi:[1,0]
	v_pk_mul_f32 v[134:135], v[134:135], v[248:249] op_sel_hi:[1,0]
	v_pk_mul_f32 v[136:137], v[136:137], v[248:249] op_sel_hi:[1,0]
	v_exp_f32_e32 v188, v188
	v_exp_f32_e32 v189, v189
	v_exp_f32_e32 v190, v190
	v_exp_f32_e32 v191, v191
	v_exp_f32_e32 v192, v192
	v_exp_f32_e32 v193, v193
	v_exp_f32_e32 v194, v194
	v_exp_f32_e32 v195, v195
	v_exp_f32_e32 v130, v130
	v_exp_f32_e32 v131, v131
	v_exp_f32_e32 v132, v132
	v_exp_f32_e32 v133, v133
	v_exp_f32_e32 v134, v134
	v_exp_f32_e32 v135, v135
	v_exp_f32_e32 v136, v136
	v_exp_f32_e32 v137, v137
	v_pk_add_f32 v[188:189], v[188:189], 1.0 op_sel_hi:[1,0]
	v_pk_add_f32 v[190:191], v[190:191], 1.0 op_sel_hi:[1,0]
	v_pk_add_f32 v[192:193], v[192:193], 1.0 op_sel_hi:[1,0]
	v_pk_add_f32 v[194:195], v[194:195], 1.0 op_sel_hi:[1,0]
	v_pk_add_f32 v[130:131], v[130:131], 1.0 op_sel_hi:[1,0]
	v_pk_add_f32 v[132:133], v[132:133], 1.0 op_sel_hi:[1,0]
	v_pk_add_f32 v[134:135], v[134:135], 1.0 op_sel_hi:[1,0]
	v_pk_add_f32 v[136:137], v[136:137], 1.0 op_sel_hi:[1,0]
	v_rcp_f32_e32 v188, v188
	v_rcp_f32_e32 v189, v189
	v_rcp_f32_e32 v190, v190
	v_rcp_f32_e32 v191, v191
	v_rcp_f32_e32 v192, v192
	v_rcp_f32_e32 v193, v193
	v_rcp_f32_e32 v194, v194
	v_rcp_f32_e32 v195, v195
	v_pk_mul_f32 v[130:131], v[130:131], v[188:189]
	v_pk_mul_f32 v[132:133], v[132:133], v[190:191]
	v_pk_mul_f32 v[134:135], v[134:135], v[192:193]
	v_pk_mul_f32 v[136:137], v[136:137], v[194:195]
	v_pk_mul_f32 v[6:7], v[6:7], v[130:131]
	v_pk_mul_f32 v[8:9], v[8:9], v[132:133]
	v_pk_mul_f32 v[2:3], v[2:3], v[134:135]
	v_pk_mul_f32 v[4:5], v[4:5], v[136:137]

; DI unsigned pk2(float lo, float hi) { const f32x2 v = {lo, hi}; const bf16x2_t b = __builtin_convertvector(v, bf16x2_t); return __builtin_bit_cast(unsigned, b); }
; DI float sigmoidf_(float x) { return __builtin_amdgcn_rcpf(1.0f + __expf(-x)); }
;     DI void operator()(const Acc& acc, const Unit& u, int wr, int wc, int fr, int fq) const {
;     ...
;                 const int r = row0 + ai * 128 + m * 16;
; #pragma unroll
;                 for (int bj = 0; bj < 2; ++bj) {
;                     const int c0 = u.pn * 256 + bj * 128 + wc * 32 + 8 * fq;
;                     const u32x4 gw = *(const u32x4*)(Z + (size_t)r * NZ + ZC_GM + DM + c0);
;                     const f32x4 v0 = acc[ai][bj][m][0], v1 = acc[ai][bj][m][1];
;                     u32x4 w;
;                     w.x = pk2(v0[0] * sigmoidf_(bflo(gw.x)), v0[1] * sigmoidf_(bfhi(gw.x))); w.y = pk2(v0[2] * sigmoidf_(bflo(gw.y)), v0[3] * sigmoidf_(bfhi(gw.y)));
;                     w.z = pk2(v1[0] * sigmoidf_(bflo(gw.z)), v1[1] * sigmoidf_(bfhi(gw.z))); w.w = pk2(v1[2] * sigmoidf_(bflo(gw.w)), v1[3] * sigmoidf_(bfhi(gw.w)));
;                     *(u32x4*)(MG + (size_t)r * DM + c0) = w;
.LBB0_875:
	v_mad_u32_u24 v164, v160, s75, v158
	v_add_u32_e32 v164, 0x1a00, v164
	v_lshl_add_u32 v165, v160, 11, v158
	v_mov_b32_e32 v196, 0xbfb8aa3b
	global_load_dwordx4 v[172:175], v164, s[22:23]
	global_load_dwordx4 v[176:179], v164, s[22:23] offset:256
	v_add_u32_e32 v161, 0x22000, v164
	global_load_dwordx4 v[180:183], v161, s[22:23]
	global_load_dwordx4 v[184:187], v161, s[22:23] offset:256
	v_add_u32_e32 v161, 0x44000, v164
	global_load_dwordx4 v[188:191], v161, s[22:23]
	global_load_dwordx4 v[192:195], v161, s[22:23] offset:256
	v_add_u32_e32 v161, 0x66000, v164
	global_load_dwordx4 v[200:203], v161, s[22:23]
	global_load_dwordx4 v[204:207], v161, s[22:23] offset:256
	v_add_u32_e32 v161, 0x110000, v164
	global_load_dwordx4 v[208:211], v161, s[22:23]
	global_load_dwordx4 v[212:215], v161, s[22:23] offset:256
	v_add_u32_e32 v161, 0x132000, v164
	global_load_dwordx4 v[216:219], v161, s[22:23]
	global_load_dwordx4 v[220:223], v161, s[22:23] offset:256
	v_add_u32_e32 v161, 0x154000, v164
	global_load_dwordx4 v[224:227], v161, s[22:23]
	global_load_dwordx4 v[228:231], v161, s[22:23] offset:256
	v_add_u32_e32 v161, 0x176000, v164
	global_load_dwordx4 v[232:235], v161, s[22:23]
	global_load_dwordx4 v[236:239], v161, s[22:23] offset:256
	s_waitcnt vmcnt(14)
	v_lshlrev_b32_e32 v240, 16, v172
	v_and_b32_e32 v241, 0xffff0000, v172
	v_lshlrev_b32_e32 v242, 16, v173
	v_and_b32_e32 v243, 0xffff0000, v173
	v_lshlrev_b32_e32 v244, 16, v174
	v_and_b32_e32 v245, 0xffff0000, v174
	v_lshlrev_b32_e32 v246, 16, v175
	v_and_b32_e32 v247, 0xffff0000, v175
	v_pk_mul_f32 v[240:241], v[240:241], v[196:197] op_sel_hi:[1,0]
	v_pk_mul_f32 v[242:243], v[242:243], v[196:197] op_sel_hi:[1,0]
	v_pk_mul_f32 v[244:245], v[244:245], v[196:197] op_sel_hi:[1,0]
	v_pk_mul_f32 v[246:247], v[246:247], v[196:197] op_sel_hi:[1,0]
	v_exp_f32_e32 v240, v240
	v_exp_f32_e32 v241, v241
	v_exp_f32_e32 v242, v242
	v_exp_f32_e32 v243, v243
	v_exp_f32_e32 v244, v244
	v_exp_f32_e32 v245, v245
	v_exp_f32_e32 v246, v246
	v_exp_f32_e32 v247, v247
	v_pk_add_f32 v[240:241], v[240:241], 1.0 op_sel_hi:[1,0]
	v_pk_add_f32 v[242:243], v[242:243], 1.0 op_sel_hi:[1,0]
	v_pk_add_f32 v[244:245], v[244:245], 1.0 op_sel_hi:[1,0]
	v_pk_add_f32 v[246:247], v[246:247], 1.0 op_sel_hi:[1,0]
	v_rcp_f32_e32 v240, v240
	v_rcp_f32_e32 v241, v241
	v_rcp_f32_e32 v242, v242
	v_rcp_f32_e32 v243, v243
	v_rcp_f32_e32 v244, v244
	v_rcp_f32_e32 v245, v245
	v_rcp_f32_e32 v246, v246
	v_rcp_f32_e32 v247, v247
	v_pk_mul_f32 v[34:35], v[34:35], v[240:241]
	v_pk_mul_f32 v[36:37], v[36:37], v[242:243]
	v_pk_mul_f32 v[30:31], v[30:31], v[244:245]
	v_pk_mul_f32 v[32:33], v[32:33], v[246:247]
	v_cvt_pk_bf16_f32 v130, v34, v35
	v_cvt_pk_bf16_f32 v131, v36, v37
	v_cvt_pk_bf16_f32 v132, v30, v31
	v_cvt_pk_bf16_f32 v133, v32, v33
	global_store_dwordx4 v165, v[130:133], s[10:11]
	v_lshlrev_b32_e32 v240, 16, v176
	v_and_b32_e32 v241, 0xffff0000, v176
	v_lshlrev_b32_e32 v242, 16, v177
	v_and_b32_e32 v243, 0xffff0000, v177
	v_lshlrev_b32_e32 v244, 16, v178
	v_and_b32_e32 v245, 0xffff0000, v178
	v_lshlrev_b32_e32 v246, 16, v179
	v_and_b32_e32 v247, 0xffff0000, v179
	v_pk_mul_f32 v[240:241], v[240:241], v[196:197] op_sel_hi:[1,0]
	v_pk_mul_f32 v[242:243], v[242:243], v[196:197] op_sel_hi:[1,0]
	v_pk_mul_f32 v[244:245], v[244:245], v[196:197] op_sel_hi:[1,0]
	v_pk_mul_f32 v[246:247], v[246:247], v[196:197] op_sel_hi:[1,0]
	v_exp_f32_e32 v240, v240
	v_exp_f32_e32 v241, v241
	v_exp_f32_e32 v242, v242
	v_exp_f32_e32 v243, v243
	v_exp_f32_e32 v244, v244
	v_exp_f32_e32 v245, v245
	v_exp_f32_e32 v246, v246
	v_exp_f32_e32 v247, v247
	v_pk_add_f32 v[240:241], v[240:241], 1.0 op_sel_hi:[1,0]
	v_pk_add_f32 v[242:243], v[242:243], 1.0 op_sel_hi:[1,0]
	v_pk_add_f32 v[244:245], v[244:245], 1.0 op_sel_hi:[1,0]
	v_pk_add_f32 v[246:247], v[246:247], 1.0 op_sel_hi:[1,0]
	v_rcp_f32_e32 v240, v240
	v_rcp_f32_e32 v241, v241
	v_rcp_f32_e32 v242, v242
	v_rcp_f32_e32 v243, v243
	v_rcp_f32_e32 v244, v244
	v_rcp_f32_e32 v245, v245
	v_rcp_f32_e32 v246, v246
	v_rcp_f32_e32 v247, v247
	v_pk_mul_f32 v[50:51], v[50:51], v[240:241]
	v_pk_mul_f32 v[52:53], v[52:53], v[242:243]
	v_pk_mul_f32 v[62:63], v[62:63], v[244:245]
	v_pk_mul_f32 v[64:65], v[64:65], v[246:247]
	v_cvt_pk_bf16_f32 v134, v50, v51
	v_cvt_pk_bf16_f32 v135, v52, v53
	v_cvt_pk_bf16_f32 v136, v62, v63
	v_cvt_pk_bf16_f32 v137, v64, v65
	global_store_dwordx4 v165, v[134:137], s[10:11] offset:256
	s_waitcnt vmcnt(14)
; DI unsigned pk2(float lo, float hi) { const f32x2 v = {lo, hi}; const bf16x2_t b = __builtin_convertvector(v, bf16x2_t); return __builtin_bit_cast(unsigned, b); }
; DI float sigmoidf_(float x) { return __builtin_amdgcn_rcpf(1.0f + __expf(-x)); }
;     DI void operator()(const Acc& acc, const Unit& u, int wr, int wc, int fr, int fq) const {
;     ...
;                 const int r = row0 + ai * 128 + m * 16;
; #pragma unroll
;                 for (int bj = 0; bj < 2; ++bj) {
;                     const int c0 = u.pn * 256 + bj * 128 + wc * 32 + 8 * fq;
;                     const u32x4 gw = *(const u32x4*)(Z + (size_t)r * NZ + ZC_GM + DM + c0);
;                     const f32x4 v0 = acc[ai][bj][m][0], v1 = acc[ai][bj][m][1];
;                     u32x4 w;
;                     w.x = pk2(v0[0] * sigmoidf_(bflo(gw.x)), v0[1] * sigmoidf_(bfhi(gw.x))); w.y = pk2(v0[2] * sigmoidf_(bflo(gw.y)), v0[3] * sigmoidf_(bfhi(gw.y)));
;                     w.z = pk2(v1[0] * sigmoidf_(bflo(gw.z)), v1[1] * sigmoidf_(bfhi(gw.z))); w.w = pk2(v1[2] * sigmoidf_(bflo(gw.w)), v1[3] * sigmoidf_(bfhi(gw.w)));
;                     *(u32x4*)(MG + (size_t)r * DM + c0) = w;
	v_add_u32_e32 v161, 0x8000, v165
	v_lshlrev_b32_e32 v240, 16, v180
	v_and_b32_e32 v241, 0xffff0000, v180
	v_lshlrev_b32_e32 v242, 16, v181
	v_and_b32_e32 v243, 0xffff0000, v181
	v_lshlrev_b32_e32 v244, 16, v182
	v_and_b32_e32 v245, 0xffff0000, v182
	v_lshlrev_b32_e32 v246, 16, v183
	v_and_b32_e32 v247, 0xffff0000, v183
	v_pk_mul_f32 v[240:241], v[240:241], v[196:197] op_sel_hi:[1,0]
	v_pk_mul_f32 v[242:243], v[242:243], v[196:197] op_sel_hi:[1,0]
	v_pk_mul_f32 v[244:245], v[244:245], v[196:197] op_sel_hi:[1,0]
	v_pk_mul_f32 v[246:247], v[246:247], v[196:197] op_sel_hi:[1,0]
	v_exp_f32_e32 v240, v240
	v_exp_f32_e32 v241, v241
	v_exp_f32_e32 v242, v242
	v_exp_f32_e32 v243, v243
	v_exp_f32_e32 v244, v244
	v_exp_f32_e32 v245, v245
	v_exp_f32_e32 v246, v246
	v_exp_f32_e32 v247, v247
	v_pk_add_f32 v[240:241], v[240:241], 1.0 op_sel_hi:[1,0]
	v_pk_add_f32 v[242:243], v[242:243], 1.0 op_sel_hi:[1,0]
	v_pk_add_f32 v[244:245], v[244:245], 1.0 op_sel_hi:[1,0]
	v_pk_add_f32 v[246:247], v[246:247], 1.0 op_sel_hi:[1,0]
	v_rcp_f32_e32 v240, v240
	v_rcp_f32_e32 v241, v241
	v_rcp_f32_e32 v242, v242
	v_rcp_f32_e32 v243, v243
	v_rcp_f32_e32 v244, v244
	v_rcp_f32_e32 v245, v245
	v_rcp_f32_e32 v246, v246
	v_rcp_f32_e32 v247, v247
	v_pk_mul_f32 v[58:59], v[58:59], v[240:241]
	v_pk_mul_f32 v[60:61], v[60:61], v[242:243]
	v_pk_mul_f32 v[54:55], v[54:55], v[244:245]
	v_pk_mul_f32 v[56:57], v[56:57], v[246:247]
	v_cvt_pk_bf16_f32 v248, v58, v59
	v_cvt_pk_bf16_f32 v249, v60, v61
	v_cvt_pk_bf16_f32 v250, v54, v55
	v_cvt_pk_bf16_f32 v251, v56, v57
	global_store_dwordx4 v161, v[248:251], s[10:11]
	v_lshlrev_b32_e32 v240, 16, v184
	v_and_b32_e32 v241, 0xffff0000, v184
	v_lshlrev_b32_e32 v242, 16, v185
	v_and_b32_e32 v243, 0xffff0000, v185
	v_lshlrev_b32_e32 v244, 16, v186
	v_and_b32_e32 v245, 0xffff0000, v186
	v_lshlrev_b32_e32 v246, 16, v187
	v_and_b32_e32 v247, 0xffff0000, v187
	v_pk_mul_f32 v[240:241], v[240:241], v[196:197] op_sel_hi:[1,0]
	v_pk_mul_f32 v[242:243], v[242:243], v[196:197] op_sel_hi:[1,0]
	v_pk_mul_f32 v[244:245], v[244:245], v[196:197] op_sel_hi:[1,0]
	v_pk_mul_f32 v[246:247], v[246:247], v[196:197] op_sel_hi:[1,0]
	v_exp_f32_e32 v240, v240
	v_exp_f32_e32 v241, v241
	v_exp_f32_e32 v242, v242
	v_exp_f32_e32 v243, v243
	v_exp_f32_e32 v244, v244
	v_exp_f32_e32 v245, v245
	v_exp_f32_e32 v246, v246
	v_exp_f32_e32 v247, v247
	v_pk_add_f32 v[240:241], v[240:241], 1.0 op_sel_hi:[1,0]
	v_pk_add_f32 v[242:243], v[242:243], 1.0 op_sel_hi:[1,0]
	v_pk_add_f32 v[244:245], v[244:245], 1.0 op_sel_hi:[1,0]
	v_pk_add_f32 v[246:247], v[246:247], 1.0 op_sel_hi:[1,0]
	v_rcp_f32_e32 v240, v240
	v_rcp_f32_e32 v241, v241
	v_rcp_f32_e32 v242, v242
	v_rcp_f32_e32 v243, v243
	v_rcp_f32_e32 v244, v244
	v_rcp_f32_e32 v245, v245
	v_rcp_f32_e32 v246, v246
	v_rcp_f32_e32 v247, v247
	v_pk_mul_f32 v[66:67], v[66:67], v[240:241]
	v_pk_mul_f32 v[68:69], v[68:69], v[242:243]
	v_pk_mul_f32 v[78:79], v[78:79], v[244:245]
	v_pk_mul_f32 v[80:81], v[80:81], v[246:247]
	v_cvt_pk_bf16_f32 v130, v66, v67
	v_cvt_pk_bf16_f32 v131, v68, v69
	v_cvt_pk_bf16_f32 v132, v78, v79
	v_cvt_pk_bf16_f32 v133, v80, v81
	global_store_dwordx4 v161, v[130:133], s[10:11] offset:256
	s_waitcnt vmcnt(14)
	v_add_u32_e32 v161, 0x10000, v165
	v_lshlrev_b32_e32 v240, 16, v188
	v_and_b32_e32 v241, 0xffff0000, v188
	v_lshlrev_b32_e32 v242, 16, v189
	v_and_b32_e32 v243, 0xffff0000, v189
	v_lshlrev_b32_e32 v244, 16, v190
	v_and_b32_e32 v245, 0xffff0000, v190
	v_lshlrev_b32_e32 v246, 16, v191
	v_and_b32_e32 v247, 0xffff0000, v191
	v_pk_mul_f32 v[240:241], v[240:241], v[196:197] op_sel_hi:[1,0]
	v_pk_mul_f32 v[242:243], v[242:243], v[196:197] op_sel_hi:[1,0]
	v_pk_mul_f32 v[244:245], v[244:245], v[196:197] op_sel_hi:[1,0]
	v_pk_mul_f32 v[246:247], v[246:247], v[196:197] op_sel_hi:[1,0]
	v_exp_f32_e32 v240, v240
	v_exp_f32_e32 v241, v241
	v_exp_f32_e32 v242, v242
	v_exp_f32_e32 v243, v243
	v_exp_f32_e32 v244, v244
	v_exp_f32_e32 v245, v245
	v_exp_f32_e32 v246, v246
	v_exp_f32_e32 v247, v247
	v_pk_add_f32 v[240:241], v[240:241], 1.0 op_sel_hi:[1,0]
	v_pk_add_f32 v[242:243], v[242:243], 1.0 op_sel_hi:[1,0]
	v_pk_add_f32 v[244:245], v[244:245], 1.0 op_sel_hi:[1,0]
	v_pk_add_f32 v[246:247], v[246:247], 1.0 op_sel_hi:[1,0]
	v_rcp_f32_e32 v240, v240
	v_rcp_f32_e32 v241, v241
	v_rcp_f32_e32 v242, v242
	v_rcp_f32_e32 v243, v243
	v_rcp_f32_e32 v244, v244
	v_rcp_f32_e32 v245, v245
	v_rcp_f32_e32 v246, v246
	v_rcp_f32_e32 v247, v247
	v_pk_mul_f32 v[74:75], v[74:75], v[240:241]
	v_pk_mul_f32 v[76:77], v[76:77], v[242:243]
	v_pk_mul_f32 v[70:71], v[70:71], v[244:245]
	v_pk_mul_f32 v[72:73], v[72:73], v[246:247]
	v_cvt_pk_bf16_f32 v134, v74, v75
	v_cvt_pk_bf16_f32 v135, v76, v77
	v_cvt_pk_bf16_f32 v136, v70, v71
	v_cvt_pk_bf16_f32 v137, v72, v73
	global_store_dwordx4 v161, v[134:137], s[10:11]
	v_lshlrev_b32_e32 v240, 16, v192
	v_and_b32_e32 v241, 0xffff0000, v192
	v_lshlrev_b32_e32 v242, 16, v193
	v_and_b32_e32 v243, 0xffff0000, v193
	v_lshlrev_b32_e32 v244, 16, v194
	v_and_b32_e32 v245, 0xffff0000, v194
	v_lshlrev_b32_e32 v246, 16, v195
	v_and_b32_e32 v247, 0xffff0000, v195
	v_pk_mul_f32 v[240:241], v[240:241], v[196:197] op_sel_hi:[1,0]
	v_pk_mul_f32 v[242:243], v[242:243], v[196:197] op_sel_hi:[1,0]
	v_pk_mul_f32 v[244:245], v[244:245], v[196:197] op_sel_hi:[1,0]
	v_pk_mul_f32 v[246:247], v[246:247], v[196:197] op_sel_hi:[1,0]
	v_exp_f32_e32 v240, v240
	v_exp_f32_e32 v241, v241
	v_exp_f32_e32 v242, v242
	v_exp_f32_e32 v243, v243
	v_exp_f32_e32 v244, v244
	v_exp_f32_e32 v245, v245
	v_exp_f32_e32 v246, v246
	v_exp_f32_e32 v247, v247
	v_pk_add_f32 v[240:241], v[240:241], 1.0 op_sel_hi:[1,0]
	v_pk_add_f32 v[242:243], v[242:243], 1.0 op_sel_hi:[1,0]
	v_pk_add_f32 v[244:245], v[244:245], 1.0 op_sel_hi:[1,0]
	v_pk_add_f32 v[246:247], v[246:247], 1.0 op_sel_hi:[1,0]
	v_rcp_f32_e32 v240, v240
	v_rcp_f32_e32 v241, v241
	v_rcp_f32_e32 v242, v242
	v_rcp_f32_e32 v243, v243
	v_rcp_f32_e32 v244, v244
	v_rcp_f32_e32 v245, v245
	v_rcp_f32_e32 v246, v246
	v_rcp_f32_e32 v247, v247
	v_pk_mul_f32 v[82:83], v[82:83], v[240:241]
	v_pk_mul_f32 v[84:85], v[84:85], v[242:243]
	v_pk_mul_f32 v[102:103], v[102:103], v[244:245]
	v_pk_mul_f32 v[104:105], v[104:105], v[246:247]
	v_cvt_pk_bf16_f32 v248, v82, v83
	v_cvt_pk_bf16_f32 v249, v84, v85
	v_cvt_pk_bf16_f32 v250, v102, v103
	v_cvt_pk_bf16_f32 v251, v104, v105
	global_store_dwordx4 v161, v[248:251], s[10:11] offset:256
	s_waitcnt vmcnt(14)
; DI unsigned pk2(float lo, float hi) { const f32x2 v = {lo, hi}; const bf16x2_t b = __builtin_convertvector(v, bf16x2_t); return __builtin_bit_cast(unsigned, b); }
; DI float sigmoidf_(float x) { return __builtin_amdgcn_rcpf(1.0f + __expf(-x)); }
;     DI void operator()(const Acc& acc, const Unit& u, int wr, int wc, int fr, int fq) const {
;     ...
;                 const int r = row0 + ai * 128 + m * 16;
; #pragma unroll
;                 for (int bj = 0; bj < 2; ++bj) {
;                     const int c0 = u.pn * 256 + bj * 128 + wc * 32 + 8 * fq;
;                     const u32x4 gw = *(const u32x4*)(Z + (size_t)r * NZ + ZC_GM + DM + c0);
;                     const f32x4 v0 = acc[ai][bj][m][0], v1 = acc[ai][bj][m][1];
;                     u32x4 w;
;                     w.x = pk2(v0[0] * sigmoidf_(bflo(gw.x)), v0[1] * sigmoidf_(bfhi(gw.x))); w.y = pk2(v0[2] * sigmoidf_(bflo(gw.y)), v0[3] * sigmoidf_(bfhi(gw.y)));
;                     w.z = pk2(v1[0] * sigmoidf_(bflo(gw.z)), v1[1] * sigmoidf_(bfhi(gw.z))); w.w = pk2(v1[2] * sigmoidf_(bflo(gw.w)), v1[3] * sigmoidf_(bfhi(gw.w)));
;                     *(u32x4*)(MG + (size_t)r * DM + c0) = w;
	v_add_u32_e32 v161, 0x18000, v165
	v_lshlrev_b32_e32 v240, 16, v200
	v_and_b32_e32 v241, 0xffff0000, v200
	v_lshlrev_b32_e32 v242, 16, v201
	v_and_b32_e32 v243, 0xffff0000, v201
	v_lshlrev_b32_e32 v244, 16, v202
	v_and_b32_e32 v245, 0xffff0000, v202
	v_lshlrev_b32_e32 v246, 16, v203
	v_and_b32_e32 v247, 0xffff0000, v203
	v_pk_mul_f32 v[240:241], v[240:241], v[196:197] op_sel_hi:[1,0]
	v_pk_mul_f32 v[242:243], v[242:243], v[196:197] op_sel_hi:[1,0]
	v_pk_mul_f32 v[244:245], v[244:245], v[196:197] op_sel_hi:[1,0]
	v_pk_mul_f32 v[246:247], v[246:247], v[196:197] op_sel_hi:[1,0]
	v_exp_f32_e32 v240, v240
	v_exp_f32_e32 v241, v241
	v_exp_f32_e32 v242, v242
	v_exp_f32_e32 v243, v243
	v_exp_f32_e32 v244, v244
	v_exp_f32_e32 v245, v245
	v_exp_f32_e32 v246, v246
	v_exp_f32_e32 v247, v247
	v_pk_add_f32 v[240:241], v[240:241], 1.0 op_sel_hi:[1,0]
	v_pk_add_f32 v[242:243], v[242:243], 1.0 op_sel_hi:[1,0]
	v_pk_add_f32 v[244:245], v[244:245], 1.0 op_sel_hi:[1,0]
	v_pk_add_f32 v[246:247], v[246:247], 1.0 op_sel_hi:[1,0]
	v_rcp_f32_e32 v240, v240
	v_rcp_f32_e32 v241, v241
	v_rcp_f32_e32 v242, v242
	v_rcp_f32_e32 v243, v243
	v_rcp_f32_e32 v244, v244
	v_rcp_f32_e32 v245, v245
	v_rcp_f32_e32 v246, v246
	v_rcp_f32_e32 v247, v247
	v_pk_mul_f32 v[110:111], v[110:111], v[240:241]
	v_pk_mul_f32 v[112:113], v[112:113], v[242:243]
	v_pk_mul_f32 v[106:107], v[106:107], v[244:245]
	v_pk_mul_f32 v[108:109], v[108:109], v[246:247]
	v_cvt_pk_bf16_f32 v130, v110, v111
	v_cvt_pk_bf16_f32 v131, v112, v113
	v_cvt_pk_bf16_f32 v132, v106, v107
	v_cvt_pk_bf16_f32 v133, v108, v109
	global_store_dwordx4 v161, v[130:133], s[10:11]
	v_lshlrev_b32_e32 v240, 16, v204
	v_and_b32_e32 v241, 0xffff0000, v204
	v_lshlrev_b32_e32 v242, 16, v205
	v_and_b32_e32 v243, 0xffff0000, v205
	v_lshlrev_b32_e32 v244, 16, v206
	v_and_b32_e32 v245, 0xffff0000, v206
	v_lshlrev_b32_e32 v246, 16, v207
	v_and_b32_e32 v247, 0xffff0000, v207
	v_pk_mul_f32 v[240:241], v[240:241], v[196:197] op_sel_hi:[1,0]
	v_pk_mul_f32 v[242:243], v[242:243], v[196:197] op_sel_hi:[1,0]
	v_pk_mul_f32 v[244:245], v[244:245], v[196:197] op_sel_hi:[1,0]
	v_pk_mul_f32 v[246:247], v[246:247], v[196:197] op_sel_hi:[1,0]
	v_exp_f32_e32 v240, v240
	v_exp_f32_e32 v241, v241
	v_exp_f32_e32 v242, v242
	v_exp_f32_e32 v243, v243
	v_exp_f32_e32 v244, v244
	v_exp_f32_e32 v245, v245
	v_exp_f32_e32 v246, v246
	v_exp_f32_e32 v247, v247
	v_pk_add_f32 v[240:241], v[240:241], 1.0 op_sel_hi:[1,0]
	v_pk_add_f32 v[242:243], v[242:243], 1.0 op_sel_hi:[1,0]
	v_pk_add_f32 v[244:245], v[244:245], 1.0 op_sel_hi:[1,0]
	v_pk_add_f32 v[246:247], v[246:247], 1.0 op_sel_hi:[1,0]
	v_rcp_f32_e32 v240, v240
	v_rcp_f32_e32 v241, v241
	v_rcp_f32_e32 v242, v242
	v_rcp_f32_e32 v243, v243
	v_rcp_f32_e32 v244, v244
	v_rcp_f32_e32 v245, v245
	v_rcp_f32_e32 v246, v246
	v_rcp_f32_e32 v247, v247
	v_pk_mul_f32 v[114:115], v[114:115], v[240:241]
	v_pk_mul_f32 v[116:117], v[116:117], v[242:243]
	v_pk_mul_f32 v[126:127], v[126:127], v[244:245]
	v_pk_mul_f32 v[128:129], v[128:129], v[246:247]
	v_cvt_pk_bf16_f32 v134, v114, v115
	v_cvt_pk_bf16_f32 v135, v116, v117
	v_cvt_pk_bf16_f32 v136, v126, v127
	v_cvt_pk_bf16_f32 v137, v128, v129
	global_store_dwordx4 v161, v[134:137], s[10:11] offset:256
	s_waitcnt vmcnt(14)
	v_add_u32_e32 v161, 0x40000, v165
	v_lshlrev_b32_e32 v240, 16, v208
	v_and_b32_e32 v241, 0xffff0000, v208
	v_lshlrev_b32_e32 v242, 16, v209
	v_and_b32_e32 v243, 0xffff0000, v209
	v_lshlrev_b32_e32 v244, 16, v210
	v_and_b32_e32 v245, 0xffff0000, v210
	v_lshlrev_b32_e32 v246, 16, v211
	v_and_b32_e32 v247, 0xffff0000, v211
	v_pk_mul_f32 v[240:241], v[240:241], v[196:197] op_sel_hi:[1,0]
	v_pk_mul_f32 v[242:243], v[242:243], v[196:197] op_sel_hi:[1,0]
	v_pk_mul_f32 v[244:245], v[244:245], v[196:197] op_sel_hi:[1,0]
	v_pk_mul_f32 v[246:247], v[246:247], v[196:197] op_sel_hi:[1,0]
	v_exp_f32_e32 v240, v240
	v_exp_f32_e32 v241, v241
	v_exp_f32_e32 v242, v242
	v_exp_f32_e32 v243, v243
	v_exp_f32_e32 v244, v244
	v_exp_f32_e32 v245, v245
	v_exp_f32_e32 v246, v246
	v_exp_f32_e32 v247, v247
	v_pk_add_f32 v[240:241], v[240:241], 1.0 op_sel_hi:[1,0]
	v_pk_add_f32 v[242:243], v[242:243], 1.0 op_sel_hi:[1,0]
	v_pk_add_f32 v[244:245], v[244:245], 1.0 op_sel_hi:[1,0]
	v_pk_add_f32 v[246:247], v[246:247], 1.0 op_sel_hi:[1,0]
	v_rcp_f32_e32 v240, v240
	v_rcp_f32_e32 v241, v241
	v_rcp_f32_e32 v242, v242
	v_rcp_f32_e32 v243, v243
	v_rcp_f32_e32 v244, v244
	v_rcp_f32_e32 v245, v245
	v_rcp_f32_e32 v246, v246
	v_rcp_f32_e32 v247, v247
	v_pk_mul_f32 v[122:123], v[122:123], v[240:241]
	v_pk_mul_f32 v[124:125], v[124:125], v[242:243]
	v_pk_mul_f32 v[118:119], v[118:119], v[244:245]
	v_pk_mul_f32 v[120:121], v[120:121], v[246:247]
	v_cvt_pk_bf16_f32 v248, v122, v123
	v_cvt_pk_bf16_f32 v249, v124, v125
	v_cvt_pk_bf16_f32 v250, v118, v119
	v_cvt_pk_bf16_f32 v251, v120, v121
	global_store_dwordx4 v161, v[248:251], s[10:11]
	v_lshlrev_b32_e32 v240, 16, v212
	v_and_b32_e32 v241, 0xffff0000, v212
	v_lshlrev_b32_e32 v242, 16, v213
	v_and_b32_e32 v243, 0xffff0000, v213
	v_lshlrev_b32_e32 v244, 16, v214
	v_and_b32_e32 v245, 0xffff0000, v214
	v_lshlrev_b32_e32 v246, 16, v215
	v_and_b32_e32 v247, 0xffff0000, v215
	v_pk_mul_f32 v[240:241], v[240:241], v[196:197] op_sel_hi:[1,0]
	v_pk_mul_f32 v[242:243], v[242:243], v[196:197] op_sel_hi:[1,0]
	v_pk_mul_f32 v[244:245], v[244:245], v[196:197] op_sel_hi:[1,0]
	v_pk_mul_f32 v[246:247], v[246:247], v[196:197] op_sel_hi:[1,0]
	v_exp_f32_e32 v240, v240
	v_exp_f32_e32 v241, v241
	v_exp_f32_e32 v242, v242
	v_exp_f32_e32 v243, v243
	v_exp_f32_e32 v244, v244
	v_exp_f32_e32 v245, v245
	v_exp_f32_e32 v246, v246
	v_exp_f32_e32 v247, v247
	v_pk_add_f32 v[240:241], v[240:241], 1.0 op_sel_hi:[1,0]
	v_pk_add_f32 v[242:243], v[242:243], 1.0 op_sel_hi:[1,0]
	v_pk_add_f32 v[244:245], v[244:245], 1.0 op_sel_hi:[1,0]
	v_pk_add_f32 v[246:247], v[246:247], 1.0 op_sel_hi:[1,0]
	v_rcp_f32_e32 v240, v240
	v_rcp_f32_e32 v241, v241
	v_rcp_f32_e32 v242, v242
	v_rcp_f32_e32 v243, v243
	v_rcp_f32_e32 v244, v244
	v_rcp_f32_e32 v245, v245
	v_rcp_f32_e32 v246, v246
	v_rcp_f32_e32 v247, v247
	v_pk_mul_f32 v[98:99], v[98:99], v[240:241]
	v_pk_mul_f32 v[100:101], v[100:101], v[242:243]
	v_pk_mul_f32 v[94:95], v[94:95], v[244:245]
	v_pk_mul_f32 v[96:97], v[96:97], v[246:247]
	v_cvt_pk_bf16_f32 v130, v98, v99
	v_cvt_pk_bf16_f32 v131, v100, v101
	v_cvt_pk_bf16_f32 v132, v94, v95
	v_cvt_pk_bf16_f32 v133, v96, v97
	global_store_dwordx4 v161, v[130:133], s[10:11] offset:256
	s_waitcnt vmcnt(14)
; DI unsigned pk2(float lo, float hi) { const f32x2 v = {lo, hi}; const bf16x2_t b = __builtin_convertvector(v, bf16x2_t); return __builtin_bit_cast(unsigned, b); }
; DI float sigmoidf_(float x) { return __builtin_amdgcn_rcpf(1.0f + __expf(-x)); }
;     DI void operator()(const Acc& acc, const Unit& u, int wr, int wc, int fr, int fq) const {
;     ...
;                 const int r = row0 + ai * 128 + m * 16;
; #pragma unroll
;                 for (int bj = 0; bj < 2; ++bj) {
;                     const int c0 = u.pn * 256 + bj * 128 + wc * 32 + 8 * fq;
;                     const u32x4 gw = *(const u32x4*)(Z + (size_t)r * NZ + ZC_GM + DM + c0);
;                     const f32x4 v0 = acc[ai][bj][m][0], v1 = acc[ai][bj][m][1];
;                     u32x4 w;
;                     w.x = pk2(v0[0] * sigmoidf_(bflo(gw.x)), v0[1] * sigmoidf_(bfhi(gw.x))); w.y = pk2(v0[2] * sigmoidf_(bflo(gw.y)), v0[3] * sigmoidf_(bfhi(gw.y)));
;                     w.z = pk2(v1[0] * sigmoidf_(bflo(gw.z)), v1[1] * sigmoidf_(bfhi(gw.z))); w.w = pk2(v1[2] * sigmoidf_(bflo(gw.w)), v1[3] * sigmoidf_(bfhi(gw.w)));
;                     *(u32x4*)(MG + (size_t)r * DM + c0) = w;
	v_add_u32_e32 v161, 0x48000, v165
	v_lshlrev_b32_e32 v240, 16, v216
	v_and_b32_e32 v241, 0xffff0000, v216
	v_lshlrev_b32_e32 v242, 16, v217
	v_and_b32_e32 v243, 0xffff0000, v217
	v_lshlrev_b32_e32 v244, 16, v218
	v_and_b32_e32 v245, 0xffff0000, v218
	v_lshlrev_b32_e32 v246, 16, v219
	v_and_b32_e32 v247, 0xffff0000, v219
	v_pk_mul_f32 v[240:241], v[240:241], v[196:197] op_sel_hi:[1,0]
	v_pk_mul_f32 v[242:243], v[242:243], v[196:197] op_sel_hi:[1,0]
	v_pk_mul_f32 v[244:245], v[244:245], v[196:197] op_sel_hi:[1,0]
	v_pk_mul_f32 v[246:247], v[246:247], v[196:197] op_sel_hi:[1,0]
	v_exp_f32_e32 v240, v240
	v_exp_f32_e32 v241, v241
	v_exp_f32_e32 v242, v242
	v_exp_f32_e32 v243, v243
	v_exp_f32_e32 v244, v244
	v_exp_f32_e32 v245, v245
	v_exp_f32_e32 v246, v246
	v_exp_f32_e32 v247, v247
	v_pk_add_f32 v[240:241], v[240:241], 1.0 op_sel_hi:[1,0]
	v_pk_add_f32 v[242:243], v[242:243], 1.0 op_sel_hi:[1,0]
	v_pk_add_f32 v[244:245], v[244:245], 1.0 op_sel_hi:[1,0]
	v_pk_add_f32 v[246:247], v[246:247], 1.0 op_sel_hi:[1,0]
	v_rcp_f32_e32 v240, v240
	v_rcp_f32_e32 v241, v241
	v_rcp_f32_e32 v242, v242
	v_rcp_f32_e32 v243, v243
	v_rcp_f32_e32 v244, v244
	v_rcp_f32_e32 v245, v245
	v_rcp_f32_e32 v246, v246
	v_rcp_f32_e32 v247, v247
	v_pk_mul_f32 v[90:91], v[90:91], v[240:241]
	v_pk_mul_f32 v[92:93], v[92:93], v[242:243]
	v_pk_mul_f32 v[86:87], v[86:87], v[244:245]
	v_pk_mul_f32 v[88:89], v[88:89], v[246:247]
	v_cvt_pk_bf16_f32 v134, v90, v91
	v_cvt_pk_bf16_f32 v135, v92, v93
	v_cvt_pk_bf16_f32 v136, v86, v87
	v_cvt_pk_bf16_f32 v137, v88, v89
	global_store_dwordx4 v161, v[134:137], s[10:11]
	v_lshlrev_b32_e32 v240, 16, v220
	v_and_b32_e32 v241, 0xffff0000, v220
	v_lshlrev_b32_e32 v242, 16, v221
	v_and_b32_e32 v243, 0xffff0000, v221
	v_lshlrev_b32_e32 v244, 16, v222
	v_and_b32_e32 v245, 0xffff0000, v222
	v_lshlrev_b32_e32 v246, 16, v223
	v_and_b32_e32 v247, 0xffff0000, v223
	v_pk_mul_f32 v[240:241], v[240:241], v[196:197] op_sel_hi:[1,0]
	v_pk_mul_f32 v[242:243], v[242:243], v[196:197] op_sel_hi:[1,0]
	v_pk_mul_f32 v[244:245], v[244:245], v[196:197] op_sel_hi:[1,0]
	v_pk_mul_f32 v[246:247], v[246:247], v[196:197] op_sel_hi:[1,0]
	v_exp_f32_e32 v240, v240
	v_exp_f32_e32 v241, v241
	v_exp_f32_e32 v242, v242
	v_exp_f32_e32 v243, v243
	v_exp_f32_e32 v244, v244
	v_exp_f32_e32 v245, v245
	v_exp_f32_e32 v246, v246
	v_exp_f32_e32 v247, v247
	v_pk_add_f32 v[240:241], v[240:241], 1.0 op_sel_hi:[1,0]
	v_pk_add_f32 v[242:243], v[242:243], 1.0 op_sel_hi:[1,0]
	v_pk_add_f32 v[244:245], v[244:245], 1.0 op_sel_hi:[1,0]
	v_pk_add_f32 v[246:247], v[246:247], 1.0 op_sel_hi:[1,0]
	v_rcp_f32_e32 v240, v240
	v_rcp_f32_e32 v241, v241
	v_rcp_f32_e32 v242, v242
	v_rcp_f32_e32 v243, v243
	v_rcp_f32_e32 v244, v244
	v_rcp_f32_e32 v245, v245
	v_rcp_f32_e32 v246, v246
	v_rcp_f32_e32 v247, v247
	v_pk_mul_f32 v[46:47], v[46:47], v[240:241]
	v_pk_mul_f32 v[48:49], v[48:49], v[242:243]
	v_pk_mul_f32 v[42:43], v[42:43], v[244:245]
	v_pk_mul_f32 v[44:45], v[44:45], v[246:247]
	v_cvt_pk_bf16_f32 v248, v46, v47
	v_cvt_pk_bf16_f32 v249, v48, v49
	v_cvt_pk_bf16_f32 v250, v42, v43
	v_cvt_pk_bf16_f32 v251, v44, v45
	global_store_dwordx4 v161, v[248:251], s[10:11] offset:256
	s_waitcnt vmcnt(14)
	v_add_u32_e32 v161, 0x50000, v165
	v_lshlrev_b32_e32 v240, 16, v224
	v_and_b32_e32 v241, 0xffff0000, v224
	v_lshlrev_b32_e32 v242, 16, v225
	v_and_b32_e32 v243, 0xffff0000, v225
	v_lshlrev_b32_e32 v244, 16, v226
	v_and_b32_e32 v245, 0xffff0000, v226
	v_lshlrev_b32_e32 v246, 16, v227
	v_and_b32_e32 v247, 0xffff0000, v227
	v_pk_mul_f32 v[240:241], v[240:241], v[196:197] op_sel_hi:[1,0]
	v_pk_mul_f32 v[242:243], v[242:243], v[196:197] op_sel_hi:[1,0]
	v_pk_mul_f32 v[244:245], v[244:245], v[196:197] op_sel_hi:[1,0]
	v_pk_mul_f32 v[246:247], v[246:247], v[196:197] op_sel_hi:[1,0]
	v_exp_f32_e32 v240, v240
	v_exp_f32_e32 v241, v241
	v_exp_f32_e32 v242, v242
	v_exp_f32_e32 v243, v243
	v_exp_f32_e32 v244, v244
	v_exp_f32_e32 v245, v245
	v_exp_f32_e32 v246, v246
	v_exp_f32_e32 v247, v247
	v_pk_add_f32 v[240:241], v[240:241], 1.0 op_sel_hi:[1,0]
	v_pk_add_f32 v[242:243], v[242:243], 1.0 op_sel_hi:[1,0]
	v_pk_add_f32 v[244:245], v[244:245], 1.0 op_sel_hi:[1,0]
	v_pk_add_f32 v[246:247], v[246:247], 1.0 op_sel_hi:[1,0]
	v_rcp_f32_e32 v240, v240
	v_rcp_f32_e32 v241, v241
	v_rcp_f32_e32 v242, v242
	v_rcp_f32_e32 v243, v243
	v_rcp_f32_e32 v244, v244
	v_rcp_f32_e32 v245, v245
	v_rcp_f32_e32 v246, v246
	v_rcp_f32_e32 v247, v247
	v_pk_mul_f32 v[38:39], v[38:39], v[240:241]
	v_pk_mul_f32 v[40:41], v[40:41], v[242:243]
	v_pk_mul_f32 v[26:27], v[26:27], v[244:245]
	v_pk_mul_f32 v[28:29], v[28:29], v[246:247]
	v_cvt_pk_bf16_f32 v130, v38, v39
	v_cvt_pk_bf16_f32 v131, v40, v41
	v_cvt_pk_bf16_f32 v132, v26, v27
	v_cvt_pk_bf16_f32 v133, v28, v29
	global_store_dwordx4 v161, v[130:133], s[10:11]
	v_lshlrev_b32_e32 v240, 16, v228
	v_and_b32_e32 v241, 0xffff0000, v228
	v_lshlrev_b32_e32 v242, 16, v229
	v_and_b32_e32 v243, 0xffff0000, v229
	v_lshlrev_b32_e32 v244, 16, v230
	v_and_b32_e32 v245, 0xffff0000, v230
	v_lshlrev_b32_e32 v246, 16, v231
	v_and_b32_e32 v247, 0xffff0000, v231
	v_pk_mul_f32 v[240:241], v[240:241], v[196:197] op_sel_hi:[1,0]
	v_pk_mul_f32 v[242:243], v[242:243], v[196:197] op_sel_hi:[1,0]
	v_pk_mul_f32 v[244:245], v[244:245], v[196:197] op_sel_hi:[1,0]
	v_pk_mul_f32 v[246:247], v[246:247], v[196:197] op_sel_hi:[1,0]
	v_exp_f32_e32 v240, v240
	v_exp_f32_e32 v241, v241
	v_exp_f32_e32 v242, v242
	v_exp_f32_e32 v243, v243
	v_exp_f32_e32 v244, v244
	v_exp_f32_e32 v245, v245
	v_exp_f32_e32 v246, v246
	v_exp_f32_e32 v247, v247
	v_pk_add_f32 v[240:241], v[240:241], 1.0 op_sel_hi:[1,0]
	v_pk_add_f32 v[242:243], v[242:243], 1.0 op_sel_hi:[1,0]
	v_pk_add_f32 v[244:245], v[244:245], 1.0 op_sel_hi:[1,0]
	v_pk_add_f32 v[246:247], v[246:247], 1.0 op_sel_hi:[1,0]
	v_rcp_f32_e32 v240, v240
	v_rcp_f32_e32 v241, v241
	v_rcp_f32_e32 v242, v242
	v_rcp_f32_e32 v243, v243
	v_rcp_f32_e32 v244, v244
	v_rcp_f32_e32 v245, v245
	v_rcp_f32_e32 v246, v246
	v_rcp_f32_e32 v247, v247
	v_pk_mul_f32 v[22:23], v[22:23], v[240:241]
	v_pk_mul_f32 v[24:25], v[24:25], v[242:243]
	v_pk_mul_f32 v[18:19], v[18:19], v[244:245]
	v_pk_mul_f32 v[20:21], v[20:21], v[246:247]
	v_cvt_pk_bf16_f32 v134, v22, v23
	v_cvt_pk_bf16_f32 v135, v24, v25
	v_cvt_pk_bf16_f32 v136, v18, v19
	v_cvt_pk_bf16_f32 v137, v20, v21
	global_store_dwordx4 v161, v[134:137], s[10:11] offset:256
	s_waitcnt vmcnt(14)
; DI unsigned pk2(float lo, float hi) { const f32x2 v = {lo, hi}; const bf16x2_t b = __builtin_convertvector(v, bf16x2_t); return __builtin_bit_cast(unsigned, b); }
; DI float sigmoidf_(float x) { return __builtin_amdgcn_rcpf(1.0f + __expf(-x)); }
;     DI void operator()(const Acc& acc, const Unit& u, int wr, int wc, int fr, int fq) const {
;     ...
;                 const int r = row0 + ai * 128 + m * 16;
; #pragma unroll
;                 for (int bj = 0; bj < 2; ++bj) {
;                     const int c0 = u.pn * 256 + bj * 128 + wc * 32 + 8 * fq;
;                     const u32x4 gw = *(const u32x4*)(Z + (size_t)r * NZ + ZC_GM + DM + c0);
;                     const f32x4 v0 = acc[ai][bj][m][0], v1 = acc[ai][bj][m][1];
;                     u32x4 w;
;                     w.x = pk2(v0[0] * sigmoidf_(bflo(gw.x)), v0[1] * sigmoidf_(bfhi(gw.x))); w.y = pk2(v0[2] * sigmoidf_(bflo(gw.y)), v0[3] * sigmoidf_(bfhi(gw.y)));
;                     w.z = pk2(v1[0] * sigmoidf_(bflo(gw.z)), v1[1] * sigmoidf_(bfhi(gw.z))); w.w = pk2(v1[2] * sigmoidf_(bflo(gw.w)), v1[3] * sigmoidf_(bfhi(gw.w)));
;                     *(u32x4*)(MG + (size_t)r * DM + c0) = w;
	v_add_u32_e32 v161, 0x58000, v165
	v_lshlrev_b32_e32 v240, 16, v232
	v_and_b32_e32 v241, 0xffff0000, v232
	v_lshlrev_b32_e32 v242, 16, v233
	v_and_b32_e32 v243, 0xffff0000, v233
	v_lshlrev_b32_e32 v244, 16, v234
	v_and_b32_e32 v245, 0xffff0000, v234
	v_lshlrev_b32_e32 v246, 16, v235
	v_and_b32_e32 v247, 0xffff0000, v235
	v_pk_mul_f32 v[240:241], v[240:241], v[196:197] op_sel_hi:[1,0]
	v_pk_mul_f32 v[242:243], v[242:243], v[196:197] op_sel_hi:[1,0]
	v_pk_mul_f32 v[244:245], v[244:245], v[196:197] op_sel_hi:[1,0]
	v_pk_mul_f32 v[246:247], v[246:247], v[196:197] op_sel_hi:[1,0]
	v_exp_f32_e32 v240, v240
	v_exp_f32_e32 v241, v241
	v_exp_f32_e32 v242, v242
	v_exp_f32_e32 v243, v243
	v_exp_f32_e32 v244, v244
	v_exp_f32_e32 v245, v245
	v_exp_f32_e32 v246, v246
	v_exp_f32_e32 v247, v247
	v_pk_add_f32 v[240:241], v[240:241], 1.0 op_sel_hi:[1,0]
	v_pk_add_f32 v[242:243], v[242:243], 1.0 op_sel_hi:[1,0]
	v_pk_add_f32 v[244:245], v[244:245], 1.0 op_sel_hi:[1,0]
	v_pk_add_f32 v[246:247], v[246:247], 1.0 op_sel_hi:[1,0]
	v_rcp_f32_e32 v240, v240
	v_rcp_f32_e32 v241, v241
	v_rcp_f32_e32 v242, v242
	v_rcp_f32_e32 v243, v243
	v_rcp_f32_e32 v244, v244
	v_rcp_f32_e32 v245, v245
	v_rcp_f32_e32 v246, v246
	v_rcp_f32_e32 v247, v247
	v_pk_mul_f32 v[14:15], v[14:15], v[240:241]
	v_pk_mul_f32 v[16:17], v[16:17], v[242:243]
	v_pk_mul_f32 v[10:11], v[10:11], v[244:245]
	v_pk_mul_f32 v[12:13], v[12:13], v[246:247]
	v_cvt_pk_bf16_f32 v248, v14, v15
	v_cvt_pk_bf16_f32 v249, v16, v17
	v_cvt_pk_bf16_f32 v250, v10, v11
	v_cvt_pk_bf16_f32 v251, v12, v13
	global_store_dwordx4 v161, v[248:251], s[10:11]
	v_lshlrev_b32_e32 v240, 16, v236
	v_and_b32_e32 v241, 0xffff0000, v236
	v_lshlrev_b32_e32 v242, 16, v237
	v_and_b32_e32 v243, 0xffff0000, v237
	v_lshlrev_b32_e32 v244, 16, v238
	v_and_b32_e32 v245, 0xffff0000, v238
	v_lshlrev_b32_e32 v246, 16, v239
	v_and_b32_e32 v247, 0xffff0000, v239
	v_pk_mul_f32 v[240:241], v[240:241], v[196:197] op_sel_hi:[1,0]
	v_pk_mul_f32 v[242:243], v[242:243], v[196:197] op_sel_hi:[1,0]
	v_pk_mul_f32 v[244:245], v[244:245], v[196:197] op_sel_hi:[1,0]
	v_pk_mul_f32 v[246:247], v[246:247], v[196:197] op_sel_hi:[1,0]
	v_exp_f32_e32 v240, v240
	v_exp_f32_e32 v241, v241
	v_exp_f32_e32 v242, v242
	v_exp_f32_e32 v243, v243
	v_exp_f32_e32 v244, v244
	v_exp_f32_e32 v245, v245
	v_exp_f32_e32 v246, v246
	v_exp_f32_e32 v247, v247
	v_pk_add_f32 v[240:241], v[240:241], 1.0 op_sel_hi:[1,0]
	v_pk_add_f32 v[242:243], v[242:243], 1.0 op_sel_hi:[1,0]
	v_pk_add_f32 v[244:245], v[244:245], 1.0 op_sel_hi:[1,0]
	v_pk_add_f32 v[246:247], v[246:247], 1.0 op_sel_hi:[1,0]
	v_rcp_f32_e32 v240, v240
	v_rcp_f32_e32 v241, v241
	v_rcp_f32_e32 v242, v242
	v_rcp_f32_e32 v243, v243
	v_rcp_f32_e32 v244, v244
	v_rcp_f32_e32 v245, v245
	v_rcp_f32_e32 v246, v246
	v_rcp_f32_e32 v247, v247
	v_pk_mul_f32 v[6:7], v[6:7], v[240:241]
	v_pk_mul_f32 v[8:9], v[8:9], v[242:243]
	v_pk_mul_f32 v[2:3], v[2:3], v[244:245]
	v_pk_mul_f32 v[4:5], v[4:5], v[246:247]
	v_cvt_pk_bf16_f32 v130, v6, v7
	v_cvt_pk_bf16_f32 v131, v8, v9
	v_cvt_pk_bf16_f32 v132, v2, v3
	v_cvt_pk_bf16_f32 v133, v4, v5
	global_store_dwordx4 v161, v[130:133], s[10:11] offset:256
	s_andn2_b64 vcc, exec, s[4:5]
	s_mov_b64 s[4:5], -1
	s_load_dwordx4 s[88:91], s[0:1], 0x0
	s_cbranch_vccnz .LBB0_862
	s_andn2_b64 vcc, exec, s[8:9]
	s_cbranch_vccnz .LBB0_861
	s_barrier
	s_branch .LBB0_861
